# MLP1 also regrouped (member i computes column tiles 4i..4i+3 of the group's 4 panels; HB A-operand shared through L2); +1 group barrier
# speedup vs baseline: 1.0439x; 1.0041x over previous
; __device__ __forceinline__ float bflo(unsigned w) { return __uint_as_float(w << 16); }
; __device__ __forceinline__ float bfhi(unsigned w) { return __uint_as_float(w & 0xffff0000u); }
; __device__ __forceinline__ void ln_panel_b(bf16_t* hb, float* outf, const float* gam, const float* bet) {
;     ...
; #pragma unroll
;         for (int b = 0; b < NB; ++b)
; #pragma unroll
;             for (int j = 0; j < 2; ++j)
; #pragma unroll
;                 for (int k = 0; k < 4; ++k) { v[b][8 * j + 2 * k] = bflo(nxt[b][j][k]); v[b][8 * j + 2 * k + 1] = bfhi(nxt[b][j][k]); }
;         if (it + 1 < 32 / NB) {
; #pragma unroll
;             for (int b = 0; b < NB; ++b)
; #pragma unroll
;                 for (int j = 0; j < 2; ++j) nxt[b][j] = ((const u32x4*)(hb + (size_t)(r + NB + b) * DM))[lane + 64 * j];
;         }
;         float s[NB], s2[NB];
; #pragma unroll
;         for (int b = 0; b < NB; ++b) { s[b] = 0.f;
; #pragma unroll
;             for (int k = 0; k < 16; ++k) s[b] += v[b][k]; }
; #pragma unroll
;         for (int o = 1; o < 64; o <<= 1)
; #pragma unroll
;             for (int b = 0; b < NB; ++b) s[b] += __shfl_xor(s[b], o);
; #pragma unroll
;         for (int b = 0; b < NB; ++b) { const float mean = s[b] * (1.f / DM); s2[b] = 0.f;
; #pragma unroll
;             for (int k = 0; k < 16; ++k) { v[b][k] -= mean; s2[b] += v[b][k] * v[b][k]; } }
; #pragma unroll
;         for (int o = 1; o < 64; o <<= 1)
; #pragma unroll
;             for (int b = 0; b < NB; ++b) s2[b] += __shfl_xor(s2[b], o);
.LBB0_425:
	s_waitcnt vmcnt(0)
	v_lshlrev_b32_e32 v0, 16, v34
	v_and_b32_e32 v51, 0xffff0000, v34
	v_add_f32_e32 v86, 0, v0
	v_lshlrev_b32_e32 v56, 16, v35
	v_add_f32_e32 v86, v86, v51
	v_and_b32_e32 v57, 0xffff0000, v35
	v_add_f32_e32 v86, v86, v56
	v_lshlrev_b32_e32 v58, 16, v36
	v_add_f32_e32 v86, v86, v57
	v_and_b32_e32 v59, 0xffff0000, v36
	v_lshlrev_b32_e32 v70, 16, v42
	v_add_f32_e32 v86, v86, v58
	v_lshlrev_b32_e32 v60, 16, v37
	v_and_b32_e32 v71, 0xffff0000, v42
	v_add_f32_e32 v86, v86, v59
	v_add_f32_e32 v87, 0, v70
	v_and_b32_e32 v61, 0xffff0000, v37
	v_lshlrev_b32_e32 v72, 16, v43
	v_add_f32_e32 v86, v86, v60
	v_add_f32_e32 v87, v87, v71
	v_lshlrev_b32_e32 v62, 16, v38
	v_and_b32_e32 v73, 0xffff0000, v43
	v_add_f32_e32 v86, v86, v61
	v_add_f32_e32 v87, v87, v72
	v_and_b32_e32 v63, 0xffff0000, v38
	v_lshlrev_b32_e32 v74, 16, v44
	v_add_f32_e32 v86, v86, v62
	v_add_f32_e32 v87, v87, v73
	v_lshlrev_b32_e32 v64, 16, v39
	v_and_b32_e32 v75, 0xffff0000, v44
	v_add_f32_e32 v86, v86, v63
	v_add_f32_e32 v87, v87, v74
	v_and_b32_e32 v65, 0xffff0000, v39
	v_lshlrev_b32_e32 v76, 16, v45
	v_add_f32_e32 v86, v86, v64
	v_add_f32_e32 v87, v87, v75
	v_lshlrev_b32_e32 v66, 16, v40
	v_and_b32_e32 v77, 0xffff0000, v45
	v_add_f32_e32 v86, v86, v65
	v_add_f32_e32 v87, v87, v76
	v_and_b32_e32 v67, 0xffff0000, v40
	v_lshlrev_b32_e32 v78, 16, v46
	v_add_f32_e32 v86, v86, v66
	v_add_f32_e32 v87, v87, v77
	v_lshlrev_b32_e32 v68, 16, v41
	v_and_b32_e32 v79, 0xffff0000, v46
	v_add_f32_e32 v86, v86, v67
	v_add_f32_e32 v87, v87, v78
	v_and_b32_e32 v69, 0xffff0000, v41
	v_lshlrev_b32_e32 v80, 16, v47
	v_add_f32_e32 v86, v86, v68
	v_add_f32_e32 v87, v87, v79
	v_and_b32_e32 v81, 0xffff0000, v47
	v_add_f32_e32 v86, v86, v69
	v_add_f32_e32 v87, v87, v80
	v_lshlrev_b32_e32 v82, 16, v48
	v_add_f32_e32 v87, v87, v81
	ds_bpermute_b32 v88, v191, v86
	v_and_b32_e32 v83, 0xffff0000, v48
	v_add_f32_e32 v87, v87, v82
	v_lshlrev_b32_e32 v84, 16, v49
	v_add_f32_e32 v87, v87, v83
	v_and_b32_e32 v85, 0xffff0000, v49
	v_add_f32_e32 v87, v87, v84
	v_add_f32_e32 v87, v87, v85
	s_waitcnt lgkmcnt(0)
	v_add_f32_e32 v86, v86, v88
	ds_bpermute_b32 v88, v191, v87
	v_lshl_add_u64 v[54:55], v[52:53], 0, s[26:27]
	s_mov_b32 s1, 0x6001000
	v_add_co_u32_e32 v46, vcc, s1, v54
	s_waitcnt lgkmcnt(0)
	v_add_f32_e32 v87, v87, v88
	ds_bpermute_b32 v88, v218, v86
	v_addc_co_u32_e32 v47, vcc, 0, v55, vcc
	global_load_dwordx4 v[34:37], v[46:47], off
	global_load_dwordx4 v[38:41], v[46:47], off offset:1024
	global_load_dwordx4 v[42:45], v[46:47], off offset:2048
	s_nop 0
	global_load_dwordx4 v[46:49], v[46:47], off offset:3072
	s_mov_b32 s1, 0x6000000
	s_waitcnt lgkmcnt(0)
	v_add_f32_e32 v86, v86, v88
	ds_bpermute_b32 v88, v218, v87
	s_add_u32 s26, s26, 0x1000
	s_addc_u32 s27, s27, 0
	s_cmpk_lg_u32 s26, 0xf000
	s_waitcnt lgkmcnt(0)
	v_add_f32_e32 v87, v87, v88
	ds_bpermute_b32 v88, v219, v86
	s_waitcnt lgkmcnt(0)
	v_add_f32_e32 v86, v86, v88
	ds_bpermute_b32 v88, v219, v87
	s_waitcnt lgkmcnt(0)
	v_add_f32_e32 v87, v87, v88
	ds_bpermute_b32 v88, v220, v86
	s_waitcnt lgkmcnt(0)
	v_add_f32_e32 v86, v86, v88
	ds_bpermute_b32 v88, v220, v87
	s_waitcnt lgkmcnt(0)
	v_add_f32_e32 v87, v87, v88
	ds_bpermute_b32 v88, v221, v86
	s_waitcnt lgkmcnt(0)
	v_add_f32_e32 v86, v86, v88
	ds_bpermute_b32 v88, v221, v87
	s_waitcnt lgkmcnt(0)
	v_add_f32_e32 v87, v87, v88
	ds_bpermute_b32 v88, v222, v86
	s_waitcnt lgkmcnt(0)
	v_add_f32_e32 v86, v86, v88
	ds_bpermute_b32 v88, v222, v87
	v_fmac_f32_e32 v51, 0xba800000, v86
	v_fmac_f32_e32 v0, 0xba800000, v86
	v_fmac_f32_e32 v56, 0xba800000, v86
	v_fmac_f32_e32 v57, 0xba800000, v86
	s_waitcnt lgkmcnt(0)
	v_add_f32_e32 v87, v87, v88
	v_mul_f32_e32 v88, v51, v51
	v_fmac_f32_e32 v88, v0, v0
	v_fmac_f32_e32 v88, v56, v56
	v_fmac_f32_e32 v88, v57, v57
	v_fmac_f32_e32 v58, 0xba800000, v86
	v_fmac_f32_e32 v88, v58, v58
	v_fmac_f32_e32 v59, 0xba800000, v86
	v_fmac_f32_e32 v71, 0xba800000, v87
	v_fmac_f32_e32 v88, v59, v59
	v_fmac_f32_e32 v60, 0xba800000, v86
	v_fmac_f32_e32 v61, 0xba800000, v86
	v_fmac_f32_e32 v62, 0xba800000, v86
	v_fmac_f32_e32 v63, 0xba800000, v86
	v_fmac_f32_e32 v64, 0xba800000, v86
	v_fmac_f32_e32 v65, 0xba800000, v86
	v_fmac_f32_e32 v66, 0xba800000, v86
	v_fmac_f32_e32 v67, 0xba800000, v86
	v_fmac_f32_e32 v68, 0xba800000, v86
	v_fmac_f32_e32 v69, 0xba800000, v86
	v_fmac_f32_e32 v70, 0xba800000, v87
	v_mul_f32_e32 v86, v71, v71
	v_fmac_f32_e32 v88, v60, v60
	v_fmac_f32_e32 v86, v70, v70
	v_fmac_f32_e32 v72, 0xba800000, v87
	v_fmac_f32_e32 v88, v61, v61
	v_fmac_f32_e32 v86, v72, v72
	v_fmac_f32_e32 v73, 0xba800000, v87
	v_fmac_f32_e32 v88, v62, v62
	v_fmac_f32_e32 v86, v73, v73
	v_fmac_f32_e32 v74, 0xba800000, v87
	v_fmac_f32_e32 v88, v63, v63
	v_fmac_f32_e32 v86, v74, v74
	v_fmac_f32_e32 v75, 0xba800000, v87
	v_fmac_f32_e32 v88, v64, v64
	v_fmac_f32_e32 v86, v75, v75
	v_fmac_f32_e32 v76, 0xba800000, v87
	v_fmac_f32_e32 v88, v65, v65
	v_fmac_f32_e32 v86, v76, v76
	v_fmac_f32_e32 v77, 0xba800000, v87
	v_fmac_f32_e32 v88, v66, v66
	v_fmac_f32_e32 v86, v77, v77
	v_fmac_f32_e32 v78, 0xba800000, v87
	v_fmac_f32_e32 v88, v67, v67
	v_fmac_f32_e32 v86, v78, v78
	v_fmac_f32_e32 v79, 0xba800000, v87
	v_fmac_f32_e32 v88, v68, v68
	v_fmac_f32_e32 v86, v79, v79
	v_fmac_f32_e32 v80, 0xba800000, v87
	v_fmac_f32_e32 v88, v69, v69
	v_fmac_f32_e32 v86, v80, v80
	v_fmac_f32_e32 v81, 0xba800000, v87
	v_fmac_f32_e32 v86, v81, v81
	v_fmac_f32_e32 v82, 0xba800000, v87
	v_fmac_f32_e32 v83, 0xba800000, v87
	v_fmac_f32_e32 v84, 0xba800000, v87
	v_fmac_f32_e32 v85, 0xba800000, v87
	ds_bpermute_b32 v87, v191, v88
	v_fmac_f32_e32 v86, v82, v82
	v_fmac_f32_e32 v86, v83, v83
	v_fmac_f32_e32 v86, v84, v84
	v_fmac_f32_e32 v86, v85, v85
	s_waitcnt lgkmcnt(0)
; __device__ __forceinline__ unsigned pk2(float lo, float hi) { unsigned r; asm("v_cvt_pk_bf16_f32 %0, %1, %2" : "=v"(r) : "v"(lo), "v"(hi)); return r; }
; __device__ __forceinline__ void ln_panel_b(bf16_t* hb, float* outf, const float* gam, const float* bet) {
;     ...
;             for (int b = 0; b < NB; ++b) s2[b] += __shfl_xor(s2[b], o);
; #pragma unroll
;         for (int b = 0; b < NB; ++b) {
;             const float rstd = 1.f / sqrtf(s2[b] * (1.f / DM) + LN_EPS);
; #pragma unroll
;             for (int j = 0; j < 2; ++j) {
;                 float o[8];
; #pragma unroll
;                 for (int k = 0; k < 8; ++k) o[k] = v[b][8 * j + k] * rstd * gv[j][k >> 2][k & 3] + bv[j][k >> 2][k & 3];
;                 if (outf) { f32x4* op = (f32x4*)(outf + (size_t)(r + b) * DM + 512 * j + 8 * lane); op[0] = (f32x4){o[0], o[1], o[2], o[3]}; op[1] = (f32x4){o[4], o[5], o[6], o[7]}; }
;                 else { u32x4 w; w.x = pk2(o[0], o[1]); w.y = pk2(o[2], o[3]); w.z = pk2(o[4], o[5]); w.w = pk2(o[6], o[7]); ((u32x4*)(hb + (size_t)(r + b) * DM))[lane + 64 * j] = w; }
;             }
	v_add_f32_e32 v87, v88, v87
	ds_bpermute_b32 v88, v191, v86
	s_waitcnt lgkmcnt(0)
	v_add_f32_e32 v86, v86, v88
	ds_bpermute_b32 v88, v218, v87
	s_waitcnt lgkmcnt(0)
	v_add_f32_e32 v87, v87, v88
	ds_bpermute_b32 v88, v218, v86
	s_waitcnt lgkmcnt(0)
	v_add_f32_e32 v86, v86, v88
	ds_bpermute_b32 v88, v219, v87
	s_waitcnt lgkmcnt(0)
	v_add_f32_e32 v87, v87, v88
	ds_bpermute_b32 v88, v219, v86
	s_waitcnt lgkmcnt(0)
	v_add_f32_e32 v86, v86, v88
	ds_bpermute_b32 v88, v220, v87
	s_waitcnt lgkmcnt(0)
	v_add_f32_e32 v87, v87, v88
	ds_bpermute_b32 v88, v220, v86
	s_waitcnt lgkmcnt(0)
	v_add_f32_e32 v86, v86, v88
	ds_bpermute_b32 v88, v221, v87
	s_waitcnt lgkmcnt(0)
	v_add_f32_e32 v87, v87, v88
	ds_bpermute_b32 v88, v221, v86
	s_waitcnt lgkmcnt(0)
	v_add_f32_e32 v86, v86, v88
	ds_bpermute_b32 v88, v222, v87
	s_waitcnt lgkmcnt(0)
	v_add_f32_e32 v87, v87, v88
	ds_bpermute_b32 v88, v222, v86
	v_fmamk_f32 v87, v87, 0x3a800000, v231
	v_cmp_gt_f32_e32 vcc, s97, v87
	s_waitcnt lgkmcnt(0)
	v_add_f32_e32 v86, v86, v88
	v_mul_f32_e32 v88, 0x4f800000, v87
	v_cndmask_b32_e32 v87, v87, v88, vcc
	v_sqrt_f32_e32 v88, v87
	s_nop 0
	v_add_u32_e32 v89, -1, v88
	v_fma_f32 v90, -v89, v88, v87
	v_cmp_ge_f32_e64 s[2:3], 0, v90
	v_add_u32_e32 v90, 1, v88
	s_nop 0
	v_cndmask_b32_e64 v89, v88, v89, s[2:3]
	v_fma_f32 v88, -v90, v88, v87
	v_cmp_lt_f32_e64 s[2:3], 0, v88
	s_nop 1
	v_cndmask_b32_e64 v88, v89, v90, s[2:3]
	v_mul_f32_e32 v89, 0x37800000, v88
	v_cndmask_b32_e32 v88, v88, v89, vcc
	v_cmp_class_f32_e32 vcc, v87, v232
	s_nop 1
	v_cndmask_b32_e32 v87, v88, v87, vcc
	v_div_scale_f32 v88, s[2:3], v87, v87, 1.0
	v_rcp_f32_e32 v89, v88
	s_nop 0
	v_fma_f32 v90, -v88, v89, 1.0
	v_fmac_f32_e32 v89, v90, v89
	v_div_scale_f32 v90, vcc, 1.0, v87, 1.0
	v_mul_f32_e32 v91, v90, v89
	v_fma_f32 v92, -v88, v91, v90
	v_fmac_f32_e32 v91, v92, v89
	v_fma_f32 v88, -v88, v91, v90
	v_div_fmas_f32 v88, v88, v89, v91
	v_div_fixup_f32 v87, v88, v87, 1.0
	v_mul_f32_e32 v56, v56, v87
	v_fma_f32 v88, v32, v56, v24
	v_mul_f32_e32 v56, v57, v87
	v_fma_f32 v57, v33, v56, v25
	v_mul_f32_e32 v56, v58, v87
	v_fma_f32 v58, v26, v56, v18
	v_mul_f32_e32 v56, v59, v87
	v_fma_f32 v59, v27, v56, v19
	v_mul_f32_e32 v56, v60, v87
	v_fma_f32 v60, v28, v56, v20
	v_mul_f32_e32 v56, v61, v87
	v_mul_f32_e32 v0, v0, v87
	v_mul_f32_e32 v51, v51, v87
	v_fma_f32 v61, v29, v56, v21
	v_cvt_pk_bf16_f32 v58, v58, v59
	v_cvt_pk_bf16_f32 v59, v60, v61
	v_add_co_u32_e32 v60, vcc, s1, v54
	v_mul_f32_e32 v54, v64, v87
	v_fma_f32 v0, v30, v0, v22
	v_fma_f32 v51, v31, v51, v23
	v_cvt_pk_bf16_f32 v56, v0, v51
	v_addc_co_u32_e32 v61, vcc, 0, v55, vcc
	v_fma_f32 v55, v16, v54, v8
	v_mul_f32_e32 v54, v65, v87
	v_cvt_pk_bf16_f32 v57, v88, v57
	global_store_dwordx4 v[60:61], v[56:59], off
	v_mul_f32_e32 v0, v62, v87
	v_fma_f32 v0, v14, v0, v6
	v_fma_f32 v56, v17, v54, v9
	v_mul_f32_e32 v54, v66, v87
	v_fma_f32 v57, v10, v54, v2
	v_mul_f32_e32 v54, v67, v87
	v_fma_f32 v58, v11, v54, v3
	v_mul_f32_e32 v54, v68, v87
	v_mul_f32_e32 v51, v63, v87
	v_fma_f32 v59, v12, v54, v4
	v_mul_f32_e32 v54, v69, v87
	v_fma_f32 v51, v15, v51, v7
	v_fma_f32 v62, v13, v54, v5
	v_cvt_pk_bf16_f32 v54, v0, v51
	v_fmamk_f32 v0, v86, 0x3a800000, v231
	v_cmp_gt_f32_e32 vcc, s97, v0
	v_mul_f32_e32 v51, 0x4f800000, v0
	v_cvt_pk_bf16_f32 v55, v55, v56
	v_cvt_pk_bf16_f32 v56, v57, v58
	v_cvt_pk_bf16_f32 v57, v59, v62
	global_store_dwordx4 v[60:61], v[54:57], off offset:1024
	v_cndmask_b32_e32 v0, v0, v51, vcc
	v_sqrt_f32_e32 v51, v0
	s_nop 0
	v_add_u32_e32 v54, -1, v51
	v_fma_f32 v55, -v54, v51, v0
	v_cmp_ge_f32_e64 s[2:3], 0, v55
	v_add_u32_e32 v55, 1, v51
	s_nop 0
	v_cndmask_b32_e64 v54, v51, v54, s[2:3]
	v_fma_f32 v51, -v55, v51, v0
	v_cmp_lt_f32_e64 s[2:3], 0, v51
	s_nop 1
	v_cndmask_b32_e64 v51, v54, v55, s[2:3]
	v_mul_f32_e32 v54, 0x37800000, v51
	v_cndmask_b32_e32 v51, v51, v54, vcc
	v_cmp_class_f32_e32 vcc, v0, v232
	s_nop 1
	v_cndmask_b32_e32 v0, v51, v0, vcc
	v_div_scale_f32 v51, s[2:3], v0, v0, 1.0
	v_rcp_f32_e32 v54, v51
	s_nop 0
	v_fma_f32 v55, -v51, v54, 1.0
	v_fmac_f32_e32 v54, v55, v54
	v_div_scale_f32 v55, vcc, 1.0, v0, 1.0
	v_mul_f32_e32 v56, v55, v54
	v_fma_f32 v57, -v51, v56, v55
	v_fmac_f32_e32 v56, v57, v54
	v_fma_f32 v51, -v51, v56, v55
	v_div_fmas_f32 v51, v51, v54, v56
	v_div_fixup_f32 v0, v51, v0, 1.0
	v_mul_f32_e32 v54, v71, v0
	v_mul_f32_e32 v55, v72, v0
	v_mul_f32_e32 v56, v73, v0
	v_mul_f32_e32 v57, v74, v0
	v_mul_f32_e32 v51, v70, v0
	v_fma_f32 v54, v31, v54, v23
	v_fma_f32 v55, v32, v55, v24
	v_fma_f32 v56, v33, v56, v25
	v_fma_f32 v57, v26, v57, v18
	v_mul_f32_e32 v58, v75, v0
	v_mul_f32_e32 v59, v76, v0
	v_mul_f32_e32 v62, v77, v0
	v_fma_f32 v51, v30, v51, v22
	v_fma_f32 v58, v27, v58, v19
	v_fma_f32 v59, v28, v59, v20
	v_fma_f32 v62, v29, v62, v21
	v_cvt_pk_bf16_f32 v54, v51, v54
	v_cvt_pk_bf16_f32 v55, v55, v56
	v_cvt_pk_bf16_f32 v56, v57, v58
	v_cvt_pk_bf16_f32 v57, v59, v62
	global_store_dwordx4 v[60:61], v[54:57], off offset:2048
	v_mul_f32_e32 v51, v78, v0
	v_mul_f32_e32 v58, v83, v0
	v_mul_f32_e32 v54, v79, v0
	v_mul_f32_e32 v55, v80, v0
	v_mul_f32_e32 v56, v81, v0
	v_mul_f32_e32 v57, v82, v0
	v_fma_f32 v54, v15, v54, v7
	v_fma_f32 v55, v16, v55, v8
	v_fma_f32 v56, v17, v56, v9
	v_fma_f32 v57, v10, v57, v2
	v_mul_f32_e32 v59, v84, v0
	v_mul_f32_e32 v0, v85, v0
	v_fma_f32 v51, v14, v51, v6
	v_fma_f32 v58, v11, v58, v3
	v_fma_f32 v59, v12, v59, v4
	v_fma_f32 v0, v13, v0, v5
	v_cvt_pk_bf16_f32 v54, v51, v54
	v_cvt_pk_bf16_f32 v55, v55, v56
	v_cvt_pk_bf16_f32 v56, v57, v58
	v_cvt_pk_bf16_f32 v57, v59, v0
	global_store_dwordx4 v[60:61], v[54:57], off offset:3072
	s_cbranch_scc1 .LBB0_425
; __device__ __forceinline__ float bflo(unsigned w) { return __uint_as_float(w << 16); }
; __device__ __forceinline__ float bfhi(unsigned w) { return __uint_as_float(w & 0xffff0000u); }
; __device__ __forceinline__ void ln_panel_b(bf16_t* hb, float* outf, const float* gam, const float* bet) {
;     ...
; #pragma unroll
;         for (int b = 0; b < NB; ++b)
; #pragma unroll
;             for (int j = 0; j < 2; ++j)
; #pragma unroll
;                 for (int k = 0; k < 4; ++k) { v[b][8 * j + 2 * k] = bflo(nxt[b][j][k]); v[b][8 * j + 2 * k + 1] = bfhi(nxt[b][j][k]); }
;         if (it + 1 < 32 / NB) {
; #pragma unroll
;             for (int b = 0; b < NB; ++b)
; #pragma unroll
;                 for (int j = 0; j < 2; ++j) nxt[b][j] = ((const u32x4*)(hb + (size_t)(r + NB + b) * DM))[lane + 64 * j];
;         }
;         float s[NB], s2[NB];
; #pragma unroll
;         for (int b = 0; b < NB; ++b) { s[b] = 0.f;
; #pragma unroll
;             for (int k = 0; k < 16; ++k) s[b] += v[b][k]; }
; #pragma unroll
;         for (int o = 1; o < 64; o <<= 1)
; #pragma unroll
;             for (int b = 0; b < NB; ++b) s[b] += __shfl_xor(s[b], o);
; #pragma unroll
;         for (int b = 0; b < NB; ++b) { const float mean = s[b] * (1.f / DM); s2[b] = 0.f;
; #pragma unroll
;             for (int k = 0; k < 16; ++k) { v[b][k] -= mean; s2[b] += v[b][k] * v[b][k]; } }
; #pragma unroll
;         for (int o = 1; o < 64; o <<= 1)
; #pragma unroll
;             for (int b = 0; b < NB; ++b) s2[b] += __shfl_xor(s2[b], o);
	s_waitcnt vmcnt(7)
	v_and_b32_e32 v65, 0xffff0000, v34
	v_lshlrev_b32_e32 v34, 16, v34
	v_add_f32_e32 v66, 0, v34
	v_and_b32_e32 v64, 0xffff0000, v35
	v_lshlrev_b32_e32 v35, 16, v35
	v_add_f32_e32 v66, v66, v65
	v_add_f32_e32 v66, v66, v35
	v_and_b32_e32 v63, 0xffff0000, v36
	v_lshlrev_b32_e32 v36, 16, v36
	v_add_f32_e32 v66, v66, v64
	s_waitcnt vmcnt(5)
	v_and_b32_e32 v57, 0xffff0000, v42
	v_lshlrev_b32_e32 v42, 16, v42
	v_add_f32_e32 v66, v66, v36
	v_and_b32_e32 v62, 0xffff0000, v37
	v_lshlrev_b32_e32 v37, 16, v37
	v_add_f32_e32 v66, v66, v63
	v_add_f32_e32 v67, 0, v42
	v_and_b32_e32 v56, 0xffff0000, v43
	v_lshlrev_b32_e32 v43, 16, v43
	v_add_f32_e32 v66, v66, v37
	v_add_f32_e32 v67, v67, v57
	v_and_b32_e32 v61, 0xffff0000, v38
	v_lshlrev_b32_e32 v38, 16, v38
	v_add_f32_e32 v66, v66, v62
	v_add_f32_e32 v67, v67, v43
	v_and_b32_e32 v55, 0xffff0000, v44
	v_lshlrev_b32_e32 v44, 16, v44
	v_add_f32_e32 v66, v66, v38
	v_add_f32_e32 v67, v67, v56
	v_and_b32_e32 v60, 0xffff0000, v39
	v_lshlrev_b32_e32 v39, 16, v39
	v_add_f32_e32 v66, v66, v61
	v_add_f32_e32 v67, v67, v44
	v_and_b32_e32 v54, 0xffff0000, v45
	v_lshlrev_b32_e32 v45, 16, v45
	v_add_f32_e32 v66, v66, v39
	v_add_f32_e32 v67, v67, v55
	v_and_b32_e32 v59, 0xffff0000, v40
	v_lshlrev_b32_e32 v40, 16, v40
	v_add_f32_e32 v66, v66, v60
	v_add_f32_e32 v67, v67, v45
	s_waitcnt vmcnt(4)
	v_and_b32_e32 v53, 0xffff0000, v46
	v_lshlrev_b32_e32 v46, 16, v46
	v_add_f32_e32 v66, v66, v40
	v_add_f32_e32 v67, v67, v54
	v_and_b32_e32 v58, 0xffff0000, v41
	v_lshlrev_b32_e32 v41, 16, v41
	v_add_f32_e32 v66, v66, v59
	v_add_f32_e32 v67, v67, v46
	v_and_b32_e32 v52, 0xffff0000, v47
	v_lshlrev_b32_e32 v47, 16, v47
	v_add_f32_e32 v66, v66, v41
	v_add_f32_e32 v67, v67, v53
	v_add_f32_e32 v66, v66, v58
	v_add_f32_e32 v67, v67, v47
	v_and_b32_e32 v51, 0xffff0000, v48
	v_lshlrev_b32_e32 v48, 16, v48
	v_add_f32_e32 v67, v67, v52
	ds_bpermute_b32 v68, v191, v66
	v_add_f32_e32 v67, v67, v48
	v_and_b32_e32 v0, 0xffff0000, v49
	v_lshlrev_b32_e32 v49, 16, v49
	v_add_f32_e32 v67, v67, v51
	v_add_f32_e32 v67, v67, v49
	v_add_f32_e32 v67, v67, v0
	s_waitcnt lgkmcnt(0)
	v_add_f32_e32 v66, v66, v68
	ds_bpermute_b32 v68, v191, v67
	s_or_b32 s10, s10, 30
	s_ashr_i32 s11, s10, 31
	v_lshlrev_b32_e32 v50, 4, v50
	s_movk_i32 s42, 0x400
	s_waitcnt lgkmcnt(0)
	v_add_f32_e32 v67, v67, v68
	ds_bpermute_b32 v68, v218, v66
	v_mov_b32_e32 v131, v1
	v_mov_b32_e32 v135, v1
	v_mov_b32_e32 v133, v1
	s_waitcnt lgkmcnt(0)
	v_add_f32_e32 v66, v66, v68
	ds_bpermute_b32 v68, v218, v67
	s_waitcnt lgkmcnt(0)
	v_add_f32_e32 v67, v67, v68
	ds_bpermute_b32 v68, v219, v66
	s_waitcnt lgkmcnt(0)
	v_add_f32_e32 v66, v66, v68
	ds_bpermute_b32 v68, v219, v67
	s_waitcnt lgkmcnt(0)
	v_add_f32_e32 v67, v67, v68
	ds_bpermute_b32 v68, v220, v66
	s_waitcnt lgkmcnt(0)
	v_add_f32_e32 v66, v66, v68
	ds_bpermute_b32 v68, v220, v67
	s_waitcnt lgkmcnt(0)
	v_add_f32_e32 v67, v67, v68
	ds_bpermute_b32 v68, v221, v66
	s_waitcnt lgkmcnt(0)
	v_add_f32_e32 v66, v66, v68
	ds_bpermute_b32 v68, v221, v67
	s_waitcnt lgkmcnt(0)
	v_add_f32_e32 v67, v67, v68
	ds_bpermute_b32 v68, v222, v66
	s_waitcnt lgkmcnt(0)
	v_add_f32_e32 v66, v66, v68
	ds_bpermute_b32 v68, v222, v67
	v_fmac_f32_e32 v65, 0xba800000, v66
	v_fmac_f32_e32 v34, 0xba800000, v66
	v_fmac_f32_e32 v35, 0xba800000, v66
	v_fmac_f32_e32 v64, 0xba800000, v66
	s_waitcnt lgkmcnt(0)
	v_add_f32_e32 v67, v67, v68
	v_mul_f32_e32 v68, v65, v65
	v_fmac_f32_e32 v68, v34, v34
	v_fmac_f32_e32 v68, v35, v35
	v_fmac_f32_e32 v68, v64, v64
	v_fmac_f32_e32 v36, 0xba800000, v66
	v_fmac_f32_e32 v68, v36, v36
	v_fmac_f32_e32 v63, 0xba800000, v66
	v_fmac_f32_e32 v57, 0xba800000, v67
	v_fmac_f32_e32 v68, v63, v63
	v_fmac_f32_e32 v37, 0xba800000, v66
	v_fmac_f32_e32 v62, 0xba800000, v66
	v_fmac_f32_e32 v38, 0xba800000, v66
	v_fmac_f32_e32 v61, 0xba800000, v66
	v_fmac_f32_e32 v39, 0xba800000, v66
	v_fmac_f32_e32 v60, 0xba800000, v66
	v_fmac_f32_e32 v40, 0xba800000, v66
	v_fmac_f32_e32 v59, 0xba800000, v66
	v_fmac_f32_e32 v41, 0xba800000, v66
	v_fmac_f32_e32 v58, 0xba800000, v66
	v_fmac_f32_e32 v42, 0xba800000, v67
	v_mul_f32_e32 v66, v57, v57
	v_fmac_f32_e32 v68, v37, v37
	v_fmac_f32_e32 v66, v42, v42
	v_fmac_f32_e32 v43, 0xba800000, v67
	v_fmac_f32_e32 v68, v62, v62
	v_fmac_f32_e32 v66, v43, v43
	v_fmac_f32_e32 v56, 0xba800000, v67
	v_fmac_f32_e32 v68, v38, v38
	v_fmac_f32_e32 v66, v56, v56
	v_fmac_f32_e32 v44, 0xba800000, v67
	v_fmac_f32_e32 v68, v61, v61
	v_fmac_f32_e32 v66, v44, v44
	v_fmac_f32_e32 v55, 0xba800000, v67
	v_fmac_f32_e32 v68, v39, v39
	v_fmac_f32_e32 v66, v55, v55
	v_fmac_f32_e32 v45, 0xba800000, v67
	v_fmac_f32_e32 v68, v60, v60
	v_fmac_f32_e32 v66, v45, v45
	v_fmac_f32_e32 v54, 0xba800000, v67
	v_fmac_f32_e32 v68, v40, v40
	v_fmac_f32_e32 v66, v54, v54
	v_fmac_f32_e32 v46, 0xba800000, v67
	v_fmac_f32_e32 v68, v59, v59
	v_fmac_f32_e32 v66, v46, v46
	v_fmac_f32_e32 v53, 0xba800000, v67
	v_fmac_f32_e32 v68, v41, v41
	v_fmac_f32_e32 v66, v53, v53
	v_fmac_f32_e32 v47, 0xba800000, v67
	v_fmac_f32_e32 v68, v58, v58
	v_fmac_f32_e32 v66, v47, v47
	v_fmac_f32_e32 v52, 0xba800000, v67
	v_fmac_f32_e32 v66, v52, v52
	v_fmac_f32_e32 v48, 0xba800000, v67
	v_fmac_f32_e32 v51, 0xba800000, v67
	v_fmac_f32_e32 v49, 0xba800000, v67
	v_fmac_f32_e32 v0, 0xba800000, v67
	ds_bpermute_b32 v67, v191, v68
	v_fmac_f32_e32 v66, v48, v48
	v_fmac_f32_e32 v66, v51, v51
	v_fmac_f32_e32 v66, v49, v49
	v_fmac_f32_e32 v66, v0, v0
	s_waitcnt lgkmcnt(0)
	v_add_f32_e32 v67, v68, v67
	ds_bpermute_b32 v68, v191, v66
	s_waitcnt lgkmcnt(0)
	v_add_f32_e32 v66, v66, v68
	ds_bpermute_b32 v68, v218, v67
	s_waitcnt lgkmcnt(0)
; __device__ __forceinline__ unsigned pk2(float lo, float hi) { unsigned r; asm("v_cvt_pk_bf16_f32 %0, %1, %2" : "=v"(r) : "v"(lo), "v"(hi)); return r; }
; __device__ __forceinline__ void block_fence() { __builtin_amdgcn_fence(__ATOMIC_RELEASE, "workgroup"); __syncthreads(); __builtin_amdgcn_fence(__ATOMIC_ACQUIRE, "workgroup"); }
; __device__ __forceinline__ void ln_panel_b(bf16_t* hb, float* outf, const float* gam, const float* bet) {
;     ...
; #pragma unroll
;         for (int b = 0; b < NB; ++b) {
;             const float rstd = 1.f / sqrtf(s2[b] * (1.f / DM) + LN_EPS);
; #pragma unroll
;             for (int j = 0; j < 2; ++j) {
;                 float o[8];
; #pragma unroll
;                 for (int k = 0; k < 8; ++k) o[k] = v[b][8 * j + k] * rstd * gv[j][k >> 2][k & 3] + bv[j][k >> 2][k & 3];
;                 if (outf) { f32x4* op = (f32x4*)(outf + (size_t)(r + b) * DM + 512 * j + 8 * lane); op[0] = (f32x4){o[0], o[1], o[2], o[3]}; op[1] = (f32x4){o[4], o[5], o[6], o[7]}; }
;                 else { u32x4 w; w.x = pk2(o[0], o[1]); w.y = pk2(o[2], o[3]); w.z = pk2(o[4], o[5]); w.w = pk2(o[6], o[7]); ((u32x4*)(hb + (size_t)(r + b) * DM))[lane + 64 * j] = w; }
;             }
; __global__ void __launch_bounds__(512, 2) fwd_megakernel(Args a) {
;     ...
;         block_fence();
	v_add_f32_e32 v67, v67, v68
	ds_bpermute_b32 v68, v218, v66
	s_waitcnt lgkmcnt(0)
	v_add_f32_e32 v66, v66, v68
	ds_bpermute_b32 v68, v219, v67
	s_waitcnt lgkmcnt(0)
	v_add_f32_e32 v67, v67, v68
	ds_bpermute_b32 v68, v219, v66
	s_waitcnt lgkmcnt(0)
	v_add_f32_e32 v66, v66, v68
	ds_bpermute_b32 v68, v220, v67
	s_waitcnt lgkmcnt(0)
	v_add_f32_e32 v67, v67, v68
	ds_bpermute_b32 v68, v220, v66
	s_waitcnt lgkmcnt(0)
	v_add_f32_e32 v66, v66, v68
	ds_bpermute_b32 v68, v221, v67
	s_waitcnt lgkmcnt(0)
	v_add_f32_e32 v67, v67, v68
	ds_bpermute_b32 v68, v221, v66
	s_waitcnt lgkmcnt(0)
	v_add_f32_e32 v66, v66, v68
	ds_bpermute_b32 v68, v222, v67
	s_waitcnt lgkmcnt(0)
	v_add_f32_e32 v67, v67, v68
	ds_bpermute_b32 v68, v222, v66
	v_fmamk_f32 v67, v67, 0x3a800000, v231
	v_cmp_gt_f32_e32 vcc, s97, v67
	s_waitcnt lgkmcnt(0)
	v_add_f32_e32 v66, v66, v68
	v_mul_f32_e32 v68, 0x4f800000, v67
	v_cndmask_b32_e32 v67, v67, v68, vcc
	v_sqrt_f32_e32 v68, v67
	s_nop 0
	v_add_u32_e32 v69, -1, v68
	v_fma_f32 v70, -v69, v68, v67
	v_cmp_ge_f32_e64 s[2:3], 0, v70
	v_add_u32_e32 v70, 1, v68
	s_nop 0
	v_cndmask_b32_e64 v69, v68, v69, s[2:3]
	v_fma_f32 v68, -v70, v68, v67
	v_cmp_lt_f32_e64 s[2:3], 0, v68
	s_nop 1
	v_cndmask_b32_e64 v68, v69, v70, s[2:3]
	v_mul_f32_e32 v69, 0x37800000, v68
	v_cndmask_b32_e32 v68, v68, v69, vcc
	v_cmp_class_f32_e32 vcc, v67, v232
	s_nop 1
	v_cndmask_b32_e32 v67, v68, v67, vcc
	v_div_scale_f32 v68, s[2:3], v67, v67, 1.0
	v_rcp_f32_e32 v69, v68
	s_lshl_b64 s[2:3], s[10:11], 11
	s_add_u32 s2, s4, s2
	s_addc_u32 s3, s5, s3
	v_fma_f32 v70, -v68, v69, 1.0
	v_fmac_f32_e32 v69, v70, v69
	v_div_scale_f32 v70, vcc, 1.0, v67, 1.0
	v_mul_f32_e32 v71, v70, v69
	v_fma_f32 v72, -v68, v71, v70
	v_fmac_f32_e32 v71, v72, v69
	v_fma_f32 v68, -v68, v71, v70
	v_div_fmas_f32 v68, v68, v69, v71
	v_div_fixup_f32 v67, v68, v67, 1.0
	v_mul_f32_e32 v34, v34, v67
	v_fma_f32 v34, v30, v34, v22
	v_mul_f32_e32 v65, v65, v67
	v_mul_f32_e32 v35, v35, v67
	v_mul_f32_e32 v36, v36, v67
	v_mul_f32_e32 v37, v37, v67
	v_fma_f32 v65, v31, v65, v23
	v_fma_f32 v35, v32, v35, v24
	v_mul_f32_e32 v64, v64, v67
	v_fma_f32 v36, v26, v36, v18
	v_mul_f32_e32 v63, v63, v67
	v_fma_f32 v37, v28, v37, v20
	v_mul_f32_e32 v62, v62, v67
	v_cvt_pk_bf16_f32 v34, v34, v65
	v_fma_f32 v64, v33, v64, v25
	v_fma_f32 v63, v27, v63, v19
	v_fma_f32 v62, v29, v62, v21
	v_cvt_pk_bf16_f32 v35, v35, v64
	v_cvt_pk_bf16_f32 v36, v36, v63
	v_cvt_pk_bf16_f32 v37, v37, v62
	global_store_dwordx4 v50, v[34:37], s[2:3]
	s_nop 1
	v_mul_f32_e32 v34, v38, v67
	v_fma_f32 v34, v14, v34, v6
	v_mul_f32_e32 v35, v61, v67
	v_mul_f32_e32 v36, v39, v67
	v_mul_f32_e32 v37, v60, v67
	v_fma_f32 v35, v15, v35, v7
	v_fma_f32 v36, v16, v36, v8
	v_fma_f32 v37, v17, v37, v9
	v_mul_f32_e32 v38, v40, v67
	v_mul_f32_e32 v39, v59, v67
	v_mul_f32_e32 v40, v41, v67
	v_mul_f32_e32 v41, v58, v67
	v_cvt_pk_bf16_f32 v34, v34, v35
	v_fma_f32 v38, v10, v38, v2
	v_fma_f32 v39, v11, v39, v3
	v_fma_f32 v40, v12, v40, v4
	v_fma_f32 v41, v13, v41, v5
	v_cvt_pk_bf16_f32 v35, v36, v37
	v_cvt_pk_bf16_f32 v36, v38, v39
	v_cvt_pk_bf16_f32 v37, v40, v41
	global_store_dwordx4 v50, v[34:37], s[2:3] offset:1024
	s_nop 1
	v_fmamk_f32 v34, v66, 0x3a800000, v231
	v_cmp_gt_f32_e32 vcc, s97, v34
	v_mul_f32_e32 v35, 0x4f800000, v34
	s_nop 0
	v_cndmask_b32_e32 v34, v34, v35, vcc
	v_sqrt_f32_e32 v35, v34
	s_nop 0
	v_add_u32_e32 v36, -1, v35
	v_fma_f32 v37, -v36, v35, v34
	v_cmp_ge_f32_e64 s[2:3], 0, v37
	v_add_u32_e32 v37, 1, v35
	s_nop 0
	v_cndmask_b32_e64 v36, v35, v36, s[2:3]
	v_fma_f32 v35, -v37, v35, v34
	v_cmp_lt_f32_e64 s[2:3], 0, v35
	s_nop 1
	v_cndmask_b32_e64 v35, v36, v37, s[2:3]
	v_mul_f32_e32 v36, 0x37800000, v35
	v_cndmask_b32_e32 v35, v35, v36, vcc
	v_cmp_class_f32_e32 vcc, v34, v232
	s_nop 1
	v_cndmask_b32_e32 v34, v35, v34, vcc
	v_div_scale_f32 v35, s[2:3], v34, v34, 1.0
	v_rcp_f32_e32 v36, v35
	s_or_b32 s2, s8, 31
	s_ashr_i32 s3, s2, 31
	s_lshl_b64 s[2:3], s[2:3], 11
	v_fma_f32 v37, -v35, v36, 1.0
	v_fmac_f32_e32 v36, v37, v36
	v_div_scale_f32 v37, vcc, 1.0, v34, 1.0
	v_mul_f32_e32 v38, v37, v36
	v_fma_f32 v39, -v35, v38, v37
	v_fmac_f32_e32 v38, v39, v36
	v_fma_f32 v35, -v35, v38, v37
	v_div_fmas_f32 v35, v35, v36, v38
	v_div_fixup_f32 v34, v35, v34, 1.0
	v_mul_f32_e32 v35, v42, v34
	v_fma_f32 v22, v30, v35, v22
	v_mul_f32_e32 v30, v57, v34
	v_fma_f32 v23, v31, v30, v23
	v_mul_f32_e32 v30, v43, v34
	v_fma_f32 v24, v32, v30, v24
	v_mul_f32_e32 v30, v56, v34
	v_fmac_f32_e32 v25, v33, v30
	v_mul_f32_e32 v30, v44, v34
	v_fma_f32 v26, v26, v30, v18
	v_mul_f32_e32 v18, v55, v34
	v_fma_f32 v27, v27, v18, v19
	v_mul_f32_e32 v18, v45, v34
	s_add_u32 s2, s4, s2
	v_fma_f32 v28, v28, v18, v20
	v_mul_f32_e32 v18, v54, v34
	s_addc_u32 s3, s5, s3
	v_fmac_f32_e32 v21, v29, v18
	v_cvt_pk_bf16_f32 v18, v22, v23
	v_cvt_pk_bf16_f32 v19, v24, v25
	v_cvt_pk_bf16_f32 v20, v26, v27
	v_cvt_pk_bf16_f32 v21, v28, v21
	global_store_dwordx4 v50, v[18:21], s[2:3]
	v_mul_f32_e32 v0, v0, v34
	v_fmac_f32_e32 v5, v13, v0
	v_mul_f32_e32 v18, v46, v34
	v_fma_f32 v6, v14, v18, v6
	v_mul_f32_e32 v14, v53, v34
	v_fma_f32 v7, v15, v14, v7
	v_mul_f32_e32 v14, v47, v34
	v_fma_f32 v8, v16, v14, v8
	v_mul_f32_e32 v14, v52, v34
	v_fmac_f32_e32 v9, v17, v14
	v_mul_f32_e32 v14, v48, v34
	v_fma_f32 v10, v10, v14, v2
	v_mul_f32_e32 v2, v51, v34
	v_fma_f32 v11, v11, v2, v3
	v_mul_f32_e32 v2, v49, v34
	v_fma_f32 v12, v12, v2, v4
	v_cvt_pk_bf16_f32 v2, v6, v7
	v_cvt_pk_bf16_f32 v3, v8, v9
	v_cvt_pk_bf16_f32 v4, v10, v11
	v_cvt_pk_bf16_f32 v5, v12, v5
	global_store_dwordx4 v50, v[2:5], s[2:3] offset:1024
	v_readlane_b32 s2, v249, 0
	v_readlane_b32 s3, v249, 1
	v_mov_b32_e32 v15, v189
	s_waitcnt vmcnt(0)
	s_barrier
	v_readfirstlane_b32 s98, v189
	s_nop 3
	s_cmp_ge_u32 s98, 64
	s_cbranch_scc1 .Lgrp_bar0_done
	s_lshr_b32 s98, s88, 21
	s_and_b32 s99, s98, 7
	s_lshr_b32 s98, s98, 5
	s_lshl_b32 s98, s98, 3
	s_or_b32 s98, s98, s99
	s_lshl_b32 s98, s98, 5
	v_readlane_b32 s99, v248, 36
	s_nop 3
	s_lshl_b32 s99, s99, 4
	s_add_u32 s98, s98, s99
	s_add_u32 s98, s98, 14336
	v_mov_b32_e32 v2, s98
	v_mov_b32_e32 v3, 1
	s_mov_b64 s[100:101], exec
	s_mov_b64 exec, 1
	buffer_wbl2 sc1
	s_waitcnt vmcnt(0)
	global_atomic_add v2, v3, s[80:81]
	s_mov_b32 s99, 0

; #define PG8_WAIT_V(n) asm volatile("s_waitcnt vmcnt(" #n ")" ::: "memory")
; #define PG8_BAR __builtin_amdgcn_s_barrier()
; template <class Epi, class Sched>
; __device__ __forceinline__ void gemm_phase(LAS unsigned char* lds, const Gemm g, const Sched& S, const Epi& E) {
;     ...
;     const int wid = __builtin_amdgcn_readfirstlane(tid >> 6), lane = tid & 63, wr = wid >> 2, wc = wid & 3, fr = lane & 15, fq = lane >> 4;
;     int K = g.K; asm volatile("" : "+s"(K));
;     const int nt = K / BK;
;     unsigned voffA[2], voffB[2];
; #pragma unroll
;     for (int i = 0; i < 2; ++i) { int R, C; stage_rc(tid * 16 + i * 8192, R, C); const int Rb = Epi::PERM ? ((R & ~31) + perm32(R & 31)) : R;
;         voffA[i] = (unsigned)(R * K + C) * 2u; voffB[i] = (unsigned)(Rb * K + C) * 2u; }
;     const size_t kstep = (size_t)(BK * 2);
;     const size_t hstep = (size_t)HALF * K * 2;
;     const size_t tstep = 2 * hstep;
;     const unsigned ldsw = (unsigned)wid * 1024u;
;     const int aoff = lds_byte(wr * 64 + fr, fq * 8), boff = lds_byte(wc * 32 + fr, fq * 8);
;     ...
;     Unit cur, nxt; int ui = 0;
;     if (!S.next(0, cur)) return;
;     f32x4 acc[2][2][4][2];
; #pragma unroll
;     for (int a = 0; a < 2; ++a)
; #pragma unroll
;         for (int b = 0; b < 2; ++b)
; #pragma unroll
;             for (int m = 0; m < 4; ++m)
; #pragma unroll
;                 for (int n = 0; n < 2; ++n) acc[a][b][m][n] = (f32x4){0.f, 0.f, 0.f, 0.f};
;     bf16x8 At[4][2], B0[2][2], B1[2][2];
;     const char* cA = (const char*)g.A + (size_t)cur.pm * tstep; const char* cB = (const char*)g.Bt + (size_t)cur.pn * tstep;
;     S.a_ready(cur);
;     PG8_STAGE(PG8_SB(0, 0), cB, voffB); PG8_STAGE(PG8_SB(0, 1), cB + hstep, voffB); PG8_STAGE(PG8_SA(0, 0), cA, voffA); PG8_STAGE(PG8_SA(0, 1), cA + hstep, voffA);
;     if (wr == 1) PG8_BAR;
;     PG8_WAIT_V(2); PG8_BAR;
;     PG8_STAGE(PG8_SB(1, 0), cB + kstep, voffB); PG8_STAGE(PG8_SA(1, 0), cA + kstep, voffA); PG8_STAGE(PG8_SB(1, 1), cB + hstep + kstep, voffB);
;     PG8_WAIT_V(6); PG8_BAR;
; __global__ void __launch_bounds__(512, 2) fwd_megakernel(Args a) {
;     ...
;             pg8::Gemm g{HBp, (const bf16_t*)(ws + WS_W1) + (size_t)l * DFF * DM, DM}; pg8::PanelOrder S{DFF / 256};
;             pg8::EpiBf16<1> E{(bf16_t*)(PB + P_HID), DFF};
.Lgrp_bar0_done:
	s_barrier
	s_load_dwordx2 s[46:47], s[2:3], 0xf8
	v_readlane_b32 s2, v249, 8
	v_lshlrev_b32_e32 v0, 4, v15
	v_add_u32_e32 v2, 0x2000, v0
	v_ashrrev_i32_e32 v3, 31, v2
	v_lshrrev_b32_e32 v3, 22, v3
	v_add_u32_e32 v3, v2, v3
	v_ashrrev_i32_e32 v3, 10, v3
	v_mul_i32_i24_e32 v4, 0x400, v3
	v_sub_u32_e32 v2, v2, v4
	v_lshrrev_b32_e32 v4, 4, v2
	v_readlane_b32 s3, v249, 9
	s_waitcnt lgkmcnt(0)
	s_add_u32 s1, s46, s2
	v_bitop3_b32 v2, v4, v2, 32 bitop3:0x6c
	s_addc_u32 s3, s47, s3
	v_readlane_b32 s4, v248, 36
	v_ashrrev_i32_e32 v4, 31, v2
	s_add_u32 s2, s1, 0x6000000
	v_readlane_b32 s5, v248, 37
	v_lshrrev_b32_e32 v4, 26, v4
	s_addc_u32 s3, s3, 0
	s_and_b32 s98, s88, 0x3000000
	s_lshr_b32 s99, s98, 2
	s_sub_u32 s2, s2, s99
	s_subb_u32 s3, s3, 0
	s_lshl_b64 s[10:11], s[4:5], 23
	v_add_u32_e32 v4, v2, v4
	v_lshlrev_b32_e32 v6, 3, v3
	s_add_u32 s1, s46, s10
	v_ashrrev_i32_e32 v5, 6, v4
	v_and_b32_e32 v6, -16, v6
	v_lshlrev_b32_e32 v3, 5, v3
	s_addc_u32 s4, s47, s11
	v_add_u32_e32 v6, v5, v6
	v_and_b32_e32 v14, 32, v3
	v_and_b32_e32 v3, 0xc0, v4
	s_add_u32 s18, s1, 0x1000000
	v_and_b32_e32 v5, 3, v5
	s_mov_b32 s1, 0x7fffffe0
	v_lshrrev_b32_e32 v7, 2, v6
	v_lshlrev_b32_e32 v8, 1, v6
	v_sub_u32_e32 v2, v2, v3
	v_and_or_b32 v5, v6, s1, v5
	v_and_b32_e32 v7, 4, v7
	v_and_b32_e32 v8, 24, v8
	v_ashrrev_i16_sdwa v2, v227, sext(v2) dst_sel:DWORD dst_unused:UNUSED_PAD src0_sel:DWORD src1_sel:BYTE_0
	v_or3_b32 v5, v5, v7, v8
	v_bfe_i32 v16, v2, 0, 16
	v_add_u32_e32 v2, v14, v16
	v_mul_lo_u32 v5, v5, s42
	v_mul_lo_u32 v17, v6, s42
	v_add_lshl_u32 v130, v5, v2, 1
	v_add_lshl_u32 v132, v2, v17, 1
	v_bfe_i32 v2, v15, 27, 1
	v_lshrrev_b32_e32 v2, 22, v2
	v_add_u32_e32 v2, v0, v2
	v_and_b32_e32 v2, 0xfffffc00, v2
	v_sub_u32_e32 v0, v0, v2
	v_lshrrev_b32_e32 v2, 4, v0
	v_ashrrev_i32_e32 v4, 31, v15
	v_bitop3_b32 v0, v2, v0, 32 bitop3:0x6c
	v_lshrrev_b32_e32 v4, 26, v4
	v_ashrrev_i32_e32 v2, 31, v0
	v_add_u32_e32 v4, v15, v4
	v_lshrrev_b32_e32 v2, 26, v2
	v_ashrrev_i32_e32 v4, 6, v4
	v_add_u32_e32 v2, v0, v2
	v_lshlrev_b32_e32 v5, 3, v4
	v_ashrrev_i32_e32 v3, 6, v2
	v_and_b32_e32 v5, -16, v5
	v_add_u32_e32 v5, v3, v5
	v_and_b32_e32 v2, 0xc0, v2
	v_readfirstlane_b32 s8, v15
	v_and_b32_e32 v3, 3, v3
	v_lshrrev_b32_e32 v6, 2, v5
	v_lshlrev_b32_e32 v7, 1, v5
	v_sub_u32_e32 v0, v0, v2
	s_addc_u32 s19, s4, 0
	s_lshr_b32 s99, s98, 3
	s_add_u32 s18, s18, s99
	s_addc_u32 s19, s19, 0
	s_ashr_i32 s9, s8, 6
	v_and_or_b32 v3, v5, s1, v3
	v_and_b32_e32 v6, 4, v6
	v_and_b32_e32 v7, 24, v7
	v_lshlrev_b32_e32 v4, 5, v4
	v_ashrrev_i16_sdwa v0, v227, sext(v0) dst_sel:DWORD dst_unused:UNUSED_PAD src0_sel:DWORD src1_sel:BYTE_0
	s_lshl_b32 s4, s9, 10
	v_or3_b32 v3, v3, v6, v7
	v_and_b32_e32 v18, 32, v4
	v_bfe_i32 v19, v0, 0, 16
	v_mul_lo_u32 v3, v3, s42
	v_add_u32_e32 v2, v18, v19
	s_add_i32 s5, s4, 0
	s_ashr_i32 s43, s42, 31
	v_add_lshl_u32 v0, v3, v2, 1
	s_add_i32 m0, s5, 0x10000
	s_ashr_i32 s36, s8, 8
	s_lshl_b64 s[26:27], s[42:43], 8
	global_load_lds_dwordx4 v0, s[18:19]
	s_add_i32 m0, s5, 0x12000
	s_add_u32 s38, s18, s26
	global_load_lds_dwordx4 v130, s[18:19]
	s_addc_u32 s39, s19, s27
	s_add_i32 m0, s5, 0x14000
	v_mul_lo_u32 v20, v5, s42
	global_load_lds_dwordx4 v0, s[38:39]
	s_add_i32 m0, s5, 0x16000
	s_add_i32 s54, s5, 0x2000
	v_add_lshl_u32 v134, v2, v20, 1
	v_lshl_add_u64 v[6:7], s[38:39], 0, v[0:1]
	v_lshl_add_u64 v[8:9], s[38:39], 0, v[130:131]
	global_load_lds_dwordx4 v130, s[38:39]
	s_mov_b32 m0, s5
	s_add_u32 s38, s2, s26
	global_load_lds_dwordx4 v134, s[2:3]
	s_mov_b32 m0, s54
	s_addc_u32 s39, s3, s27
	s_add_i32 s55, s5, 0x4000
	global_load_lds_dwordx4 v132, s[2:3]
	s_mov_b32 m0, s55
	s_add_i32 s56, s5, 0x6000
	global_load_lds_dwordx4 v134, s[38:39]
	s_mov_b32 m0, s56
	s_cmp_eq_u32 s36, 1
	global_load_lds_dwordx4 v132, s[38:39]
	v_lshl_add_u64 v[2:3], s[18:19], 0, v[0:1]
	v_lshl_add_u64 v[4:5], s[18:19], 0, v[130:131]
	v_lshl_add_u64 v[10:11], s[2:3], 0, v[134:135]
	v_lshl_add_u64 v[12:13], s[2:3], 0, v[132:133]
	s_cselect_b64 s[38:39], -1, 0
	s_cmp_lg_u32 s36, 1
	s_cbranch_scc1 .LBB0_428
	s_barrier
.LBB0_428:
	s_add_u32 s48, s46, s88
	s_addc_u32 s49, s47, s89
	s_add_i32 m0, s5, 0x18000
	v_lshl_add_u64 v[2:3], v[2:3], 0, s[6:7]
	s_waitcnt vmcnt(2)
	s_barrier
	global_load_lds_dwordx4 v[2:3], off
	v_lshl_add_u64 v[2:3], v[4:5], 0, s[6:7]
	s_add_i32 m0, s5, 0x1a000
	s_add_i32 s57, s5, 0x8000
	global_load_lds_dwordx4 v[2:3], off
	v_lshl_add_u64 v[2:3], v[10:11], 0, s[6:7]
	s_mov_b32 m0, s57
	s_add_i32 s58, s5, 0xa000
	global_load_lds_dwordx4 v[2:3], off
	v_lshl_add_u64 v[2:3], v[12:13], 0, s[6:7]
	s_mov_b32 m0, s58
	s_lshr_b32 s1, s43, 26
	global_load_lds_dwordx4 v[2:3], off
	s_add_i32 m0, s5, 0x1c000
	v_lshl_add_u64 v[2:3], v[6:7], 0, s[6:7]
	global_load_lds_dwordx4 v[2:3], off
	v_lshl_add_u64 v[2:3], v[8:9], 0, s[6:7]
	s_add_i32 m0, s5, 0x1e000
	s_add_i32 s1, s42, s1
	global_load_lds_dwordx4 v[2:3], off
	v_and_b32_e32 v3, 15, v15
	v_and_b32_e32 v4, 48, v15
	v_lshlrev_b32_e32 v5, 2, v15
	s_ashr_i32 s59, s1, 6
	v_lshl_or_b32 v2, s36, 6, v3
	v_lshl_or_b32 v3, v3, 6, v4
	s_lshl_b32 s1, s36, 13
	v_and_b32_e32 v5, 32, v5
	v_bitop3_b32 v6, v3, s1, v5 bitop3:0xde
	s_lshl_b32 s1, s9, 5
	s_and_b32 s1, s1, 0x60
	s_lshl_b64 s[40:41], s[42:43], 9
	s_lshl_b32 s9, s1, 7
	s_cmp_gt_i32 s42, 63
	v_bitop3_b32 v142, v3, s9, v5 bitop3:0xde
	s_cselect_b64 s[42:43], -1, 0
	s_add_i32 s60, s59, -2
	v_ashrrev_i32_e32 v3, 31, v2
	s_cmpk_lt_u32 s8, 0x100
	v_lshlrev_b64 v[2:3], 13, v[2:3]
	s_cselect_b64 s[44:45], -1, 0
	v_lshl_add_u64 v[2:3], s[48:49], 0, v[2:3]
	s_lshl_b32 s36, s1, 1
	v_lshl_add_u64 v[2:3], v[2:3], 0, s[36:37]
	v_mov_b32_e32 v5, v1
	v_lshl_add_u64 v[2:3], v[2:3], 0, v[4:5]
	s_mov_b64 s[8:9], 0xe000000
	v_readlane_b32 s1, v248, 14
	v_lshl_add_u64 v[136:137], v[2:3], 0, s[8:9]
	s_sub_u32 s100, 0, s98
	s_subb_u32 s101, 0, 0
	v_lshl_add_u64 v[136:137], v[136:137], 0, s[100:101]
	s_add_u32 s1, s46, s1
	v_readlane_b32 s8, v248, 15
	s_addc_u32 s9, s47, s8
	v_add_u32_e32 v2, v20, v18
	s_add_u32 s8, s1, s26
	v_add_lshl_u32 v2, v2, v19, 1
	v_mov_b32_e32 v3, v1
	s_addc_u32 s9, s9, s27
	s_lshr_b32 s99, s98, 2
	s_sub_u32 s8, s8, s99
	s_subb_u32 s9, s9, 0
	s_waitcnt vmcnt(6)
	v_lshl_add_u64 v[138:139], s[8:9], 0, v[2:3]
	v_add_u32_e32 v2, v17, v14
	v_add_lshl_u32 v2, v2, v16, 1
	v_lshl_add_u64 v[140:141], s[8:9], 0, v[2:3]
	s_mov_b32 s8, 0
	v_add_u32_e32 v143, 0, v6
	s_mov_b64 s[48:49], s[18:19]
	s_mov_b64 s[46:47], s[18:19]
	s_barrier
	s_branch .LBB0_431

; template <class Epi, class Sched>
; __device__ __forceinline__ void gemm_phase(LAS unsigned char* lds, const Gemm g, const Sched& S, const Epi& E) {
;     ...
;     for (;;) {
;         const bool has_next = S.next(ui + 1, nxt);
;         const char* nA = has_next ? (const char*)g.A + (size_t)nxt.pm * tstep : cA; const char* nB = has_next ? (const char*)g.Bt + (size_t)nxt.pn * tstep : cB;
;         for (int t = 0; t < nt; t += 2) {
;             const bool last = (t == nt - 2);
;             const char* a1 = cA + (size_t)(t + 1) * kstep;
;             const char* a2 = last ? nA : cA + (size_t)(t + 2) * kstep; const char* b2 = last ? nB : cB + (size_t)(t + 2) * kstep;
;             const char* a3 = a2 + kstep; const char* b3 = b2 + kstep;
;             if (last && has_next) S.a_ready(nxt);
.LBB0_430:
	s_andn2_b64 vcc, exec, s[8:9]
	s_add_u32 s2, s2, s100
	s_addc_u32 s3, s3, 0
	v_lshl_add_u64 v[138:139], v[138:139], 0, s[100:101]
	v_lshl_add_u64 v[140:141], v[140:141], 0, s[100:101]
	s_mov_b32 s8, s61
	s_mov_b64 s[48:49], s[46:47]
	s_cbranch_vccz .LBB0_441
.LBB0_431:
	s_add_i32 s61, s8, 1
	s_and_b32 s100, s61, 3
	s_cmp_eq_u32 s100, 0
	s_cselect_b32 s100, 0x400000, 0
	s_mov_b32 s101, 0
	s_cmp_gt_u32 s8, 14
	s_cbranch_scc1 .LBB0_433
	s_and_b32 s1, s61, 3
	s_lshl_b32 s1, s1, 19
	s_add_u32 s46, s18, s1
	s_addc_u32 s47, s19, 0

; #define PG8_STAGE(bufoff, gbase, voff) do { _Pragma("unroll") for (int _i = 0; _i < 2; ++_i) \
;         __builtin_amdgcn_global_load_lds((const unsigned*)((const char*)(gbase) + (voff)[_i]), (LAS unsigned*)(lds + (bufoff) + ldsw + _i * 8192), 16, 0, 0); } while (0)
; #define PG8_LDA(dst, b, h) do { _Pragma("unroll") for (int m = 0; m < 4; ++m) _Pragma("unroll") for (int k = 0; k < 2; ++k) dst[m][k] = *(const LAS bf16x8*)(lds + PG8_SA(b, h) + aoff + m * 2048 + k * 1024); } while (0)
; #define PG8_LDB(dst, b, h) do { _Pragma("unroll") for (int n = 0; n < 2; ++n) _Pragma("unroll") for (int k = 0; k < 2; ++k) dst[n][k] = *(const LAS bf16x8*)(lds + PG8_SB(b, h) + boff + n * 2048 + k * 1024); } while (0)
; #define PG8_MMA(ai, bj, At, Bt) do { __builtin_amdgcn_s_setprio(1); _Pragma("unroll") for (int m = 0; m < 4; ++m) _Pragma("unroll") for (int n = 0; n < 2; ++n) _Pragma("unroll") for (int k = 0; k < 2; ++k) \
;         acc[ai][bj][m][n] = __builtin_amdgcn_mfma_f32_16x16x32_bf16(Bt[n][k], At[m][k], acc[ai][bj][m][n], 0, 0, 0); __builtin_amdgcn_s_setprio(0); } while (0)
; #define PG8_WAIT_V(n) asm volatile("s_waitcnt vmcnt(" #n ")" ::: "memory")
; #define PG8_WAIT_L(n) asm volatile("s_waitcnt lgkmcnt(" #n ")" ::: "memory")
; #define PG8_BAR __builtin_amdgcn_s_barrier()
; template <class Epi, class Sched>
; __device__ __forceinline__ void gemm_phase(LAS unsigned char* lds, const Gemm g, const Sched& S, const Epi& E) {
;     ...
;         for (int t = 0; t < nt; t += 2) {
;             const bool last = (t == nt - 2);
;             const char* a1 = cA + (size_t)(t + 1) * kstep;
;             const char* a2 = last ? nA : cA + (size_t)(t + 2) * kstep; const char* b2 = last ? nB : cB + (size_t)(t + 2) * kstep;
;             const char* a3 = a2 + kstep; const char* b3 = b2 + kstep;
;             if (last && has_next) S.a_ready(nxt);
;             PG8_LDB(B0, 0, 0); PG8_LDB(B1, 0, 1); PG8_SCHED; PG8_LDA(At, 0, 0); PG8_STAGE(PG8_SA(1, 1), a1 + hstep, voffA);
;             PG8_WAIT_V(8); PG8_WAIT_L(0); PG8_BAR; PG8_MMA(0, 0, At, B0); PG8_MMA(0, 1, At, B1); PG8_BAR; PG8_SCHED;
;             PG8_LDA(At, 0, 1); PG8_STAGE(PG8_SB(0, 0), b2, voffB); PG8_STAGE(PG8_SB(0, 1), b2 + hstep, voffB); PG8_STAGE(PG8_SA(0, 0), a2, voffA);
;             PG8_WAIT_V(8); PG8_WAIT_L(0); PG8_BAR; PG8_MMA(1, 0, At, B0); PG8_MMA(1, 1, At, B1); PG8_BAR; PG8_SCHED;
.LBB0_435:
	s_add_i32 s62, s52, 2
	s_add_u32 s50, s48, 0x100
	s_addc_u32 s51, s49, 0
	s_add_u32 s1, s9, s48
	s_addc_u32 s53, s36, s49
	s_cmp_eq_u32 s60, s52
	s_cselect_b32 s52, s100, s50
	s_cselect_b32 s63, 0, s51
	s_cselect_b32 s64, s46, s1
	s_cselect_b32 s65, s47, s53
	s_add_u32 s52, s2, s52
	s_addc_u32 s53, s3, s63
	s_add_i32 s1, 0, 0x10000
	s_add_i32 s63, 0, 0x14000
	v_add_u32_e32 v156, s1, v142
	v_add_u32_e32 v172, s63, v142
	ds_read_b128 v[144:147], v156
	ds_read_b128 v[148:151], v156 offset:1024
	ds_read_b128 v[152:155], v156 offset:2048
	ds_read_b128 v[156:159], v156 offset:3072
	ds_read_b128 v[160:163], v172
	ds_read_b128 v[164:167], v172 offset:1024
	ds_read_b128 v[168:171], v172 offset:2048
	ds_read_b128 v[172:175], v172 offset:3072
	v_lshl_add_u64 v[212:213], v[138:139], 0, s[48:49]
	s_add_i32 m0, s5, 0xc000
	ds_read_b128 v[176:179], v143
	ds_read_b128 v[180:183], v143 offset:1024
	ds_read_b128 v[184:187], v143 offset:2048
	ds_read_b128 v[192:195], v143 offset:3072
	ds_read_b128 v[196:199], v143 offset:4096
	ds_read_b128 v[200:203], v143 offset:5120
	ds_read_b128 v[204:207], v143 offset:6144
	ds_read_b128 v[208:211], v143 offset:7168
	global_load_lds_dwordx4 v[212:213], off
	v_lshl_add_u64 v[212:213], v[140:141], 0, s[48:49]
	s_add_i32 m0, s5, 0xe000
	s_nop 0
	global_load_lds_dwordx4 v[212:213], off
	s_waitcnt vmcnt(8)
	s_waitcnt lgkmcnt(0)
	s_barrier
	s_setprio 1
	s_waitcnt lgkmcnt(0)
	v_mfma_f32_16x16x32_bf16 v[122:125], v[144:147], v[176:179], v[122:125]
	v_mfma_f32_16x16x32_bf16 v[126:129], v[152:155], v[176:179], v[126:129]
	v_mfma_f32_16x16x32_bf16 v[110:113], v[144:147], v[184:187], v[110:113]
	v_mfma_f32_16x16x32_bf16 v[106:109], v[152:155], v[184:187], v[106:109]
	v_mfma_f32_16x16x32_bf16 v[94:97], v[144:147], v[196:199], v[94:97]
	v_mfma_f32_16x16x32_bf16 v[90:93], v[152:155], v[196:199], v[90:93]
	v_mfma_f32_16x16x32_bf16 v[78:81], v[144:147], v[204:207], v[78:81]
	v_mfma_f32_16x16x32_bf16 v[74:77], v[152:155], v[204:207], v[74:77]
	v_mfma_f32_16x16x32_bf16 v[122:125], v[148:151], v[180:183], v[122:125]
	v_mfma_f32_16x16x32_bf16 v[126:129], v[156:159], v[180:183], v[126:129]
	v_mfma_f32_16x16x32_bf16 v[110:113], v[148:151], v[192:195], v[110:113]
	v_mfma_f32_16x16x32_bf16 v[106:109], v[156:159], v[192:195], v[106:109]
	v_mfma_f32_16x16x32_bf16 v[94:97], v[148:151], v[200:203], v[94:97]
	v_mfma_f32_16x16x32_bf16 v[90:93], v[156:159], v[200:203], v[90:93]
	v_mfma_f32_16x16x32_bf16 v[78:81], v[148:151], v[208:211], v[78:81]
	v_mfma_f32_16x16x32_bf16 v[74:77], v[156:159], v[208:211], v[74:77]
	s_setprio 0
	s_setprio 1
	v_mfma_f32_16x16x32_bf16 v[118:121], v[160:163], v[176:179], v[118:121]
	v_mfma_f32_16x16x32_bf16 v[114:117], v[168:171], v[176:179], v[114:117]
	v_mfma_f32_16x16x32_bf16 v[102:105], v[160:163], v[184:187], v[102:105]
	v_mfma_f32_16x16x32_bf16 v[98:101], v[168:171], v[184:187], v[98:101]
	v_mfma_f32_16x16x32_bf16 v[86:89], v[160:163], v[196:199], v[86:89]
	v_mfma_f32_16x16x32_bf16 v[82:85], v[168:171], v[196:199], v[82:85]
	v_mfma_f32_16x16x32_bf16 v[70:73], v[160:163], v[204:207], v[70:73]
	v_mfma_f32_16x16x32_bf16 v[66:69], v[168:171], v[204:207], v[66:69]
	v_mfma_f32_16x16x32_bf16 v[118:121], v[164:167], v[180:183], v[118:121]
	v_mfma_f32_16x16x32_bf16 v[114:117], v[172:175], v[180:183], v[114:117]
	v_mfma_f32_16x16x32_bf16 v[102:105], v[164:167], v[192:195], v[102:105]
	v_mfma_f32_16x16x32_bf16 v[98:101], v[172:175], v[192:195], v[98:101]
	v_mfma_f32_16x16x32_bf16 v[86:89], v[164:167], v[200:203], v[86:89]
	v_mfma_f32_16x16x32_bf16 v[82:85], v[172:175], v[200:203], v[82:85]
	v_mfma_f32_16x16x32_bf16 v[70:73], v[164:167], v[208:211], v[70:73]
	v_mfma_f32_16x16x32_bf16 v[66:69], v[172:175], v[208:211], v[66:69]
	s_setprio 0
	s_barrier
	s_add_i32 s1, s1, s4
	v_lshl_add_u64 v[212:213], s[64:65], 0, v[0:1]
	s_mov_b32 m0, s1
	ds_read_b128 v[176:179], v143 offset:16384
	ds_read_b128 v[180:183], v143 offset:17408
	ds_read_b128 v[184:187], v143 offset:18432
	ds_read_b128 v[192:195], v143 offset:19456
	ds_read_b128 v[196:199], v143 offset:20480
	ds_read_b128 v[200:203], v143 offset:21504
	ds_read_b128 v[204:207], v143 offset:22528
	ds_read_b128 v[208:211], v143 offset:23552
	global_load_lds_dwordx4 v[212:213], off
	s_add_i32 m0, s1, 0x2000
	s_add_u32 s48, s64, s26
	v_lshl_add_u64 v[214:215], s[64:65], 0, v[130:131]
	s_addc_u32 s49, s65, s27
	s_add_i32 s1, s63, s4
	global_load_lds_dwordx4 v[214:215], off
	v_lshl_add_u64 v[216:217], s[48:49], 0, v[0:1]
	s_mov_b32 m0, s1
	v_lshl_add_u64 v[238:239], s[48:49], 0, v[130:131]
	global_load_lds_dwordx4 v[216:217], off
	s_add_i32 m0, s1, 0x2000
	v_lshl_add_u64 v[240:241], s[52:53], 0, v[134:135]
	global_load_lds_dwordx4 v[238:239], off
	s_mov_b32 m0, s5
	v_lshl_add_u64 v[244:245], s[52:53], 0, v[132:133]
	global_load_lds_dwordx4 v[240:241], off
	s_mov_b32 m0, s54
	s_nop 0
	global_load_lds_dwordx4 v[244:245], off
	s_waitcnt vmcnt(8)
	s_waitcnt lgkmcnt(0)
	s_barrier
; #define PG8_STAGE(bufoff, gbase, voff) do { _Pragma("unroll") for (int _i = 0; _i < 2; ++_i) \
;         __builtin_amdgcn_global_load_lds((const unsigned*)((const char*)(gbase) + (voff)[_i]), (LAS unsigned*)(lds + (bufoff) + ldsw + _i * 8192), 16, 0, 0); } while (0)
; #define PG8_LDA(dst, b, h) do { _Pragma("unroll") for (int m = 0; m < 4; ++m) _Pragma("unroll") for (int k = 0; k < 2; ++k) dst[m][k] = *(const LAS bf16x8*)(lds + PG8_SA(b, h) + aoff + m * 2048 + k * 1024); } while (0)
; #define PG8_LDB(dst, b, h) do { _Pragma("unroll") for (int n = 0; n < 2; ++n) _Pragma("unroll") for (int k = 0; k < 2; ++k) dst[n][k] = *(const LAS bf16x8*)(lds + PG8_SB(b, h) + boff + n * 2048 + k * 1024); } while (0)
; #define PG8_MMA(ai, bj, At, Bt) do { __builtin_amdgcn_s_setprio(1); _Pragma("unroll") for (int m = 0; m < 4; ++m) _Pragma("unroll") for (int n = 0; n < 2; ++n) _Pragma("unroll") for (int k = 0; k < 2; ++k) \
;         acc[ai][bj][m][n] = __builtin_amdgcn_mfma_f32_16x16x32_bf16(Bt[n][k], At[m][k], acc[ai][bj][m][n], 0, 0, 0); __builtin_amdgcn_s_setprio(0); } while (0)
; #define PG8_WAIT_V(n) asm volatile("s_waitcnt vmcnt(" #n ")" ::: "memory")
; #define PG8_WAIT_L(n) asm volatile("s_waitcnt lgkmcnt(" #n ")" ::: "memory")
; #define PG8_BAR __builtin_amdgcn_s_barrier()
; #define PG8_SCHED __builtin_amdgcn_sched_barrier(0)
; template <class Epi, class Sched>
; __device__ __forceinline__ void gemm_phase(LAS unsigned char* lds, const Gemm g, const Sched& S, const Epi& E) {
;     ...
;             PG8_WAIT_V(8); PG8_WAIT_L(0); PG8_BAR; PG8_MMA(1, 0, At, B0); PG8_MMA(1, 1, At, B1); PG8_BAR; PG8_SCHED;
;             PG8_LDB(B0, 1, 0); PG8_LDB(B1, 1, 1); PG8_SCHED; PG8_LDA(At, 1, 0); PG8_STAGE(PG8_SA(0, 1), a2 + hstep, voffA);
;             PG8_WAIT_V(8); PG8_WAIT_L(0); PG8_BAR; PG8_MMA(0, 0, At, B0); PG8_MMA(0, 1, At, B1); PG8_BAR; PG8_SCHED;
	s_setprio 1
	s_waitcnt lgkmcnt(0)
	v_mfma_f32_16x16x32_bf16 v[62:65], v[144:147], v[176:179], v[62:65]
	v_mfma_f32_16x16x32_bf16 v[58:61], v[152:155], v[176:179], v[58:61]
	v_mfma_f32_16x16x32_bf16 v[46:49], v[144:147], v[184:187], v[46:49]
	v_mfma_f32_16x16x32_bf16 v[42:45], v[152:155], v[184:187], v[42:45]
	v_mfma_f32_16x16x32_bf16 v[30:33], v[144:147], v[196:199], v[30:33]
	v_mfma_f32_16x16x32_bf16 v[26:29], v[152:155], v[196:199], v[26:29]
	v_mfma_f32_16x16x32_bf16 v[14:17], v[144:147], v[204:207], v[14:17]
	v_mfma_f32_16x16x32_bf16 v[10:13], v[152:155], v[204:207], v[10:13]
	v_mfma_f32_16x16x32_bf16 v[62:65], v[148:151], v[180:183], v[62:65]
	v_mfma_f32_16x16x32_bf16 v[58:61], v[156:159], v[180:183], v[58:61]
	v_mfma_f32_16x16x32_bf16 v[46:49], v[148:151], v[192:195], v[46:49]
	v_mfma_f32_16x16x32_bf16 v[42:45], v[156:159], v[192:195], v[42:45]
	v_mfma_f32_16x16x32_bf16 v[30:33], v[148:151], v[200:203], v[30:33]
	v_mfma_f32_16x16x32_bf16 v[26:29], v[156:159], v[200:203], v[26:29]
	v_mfma_f32_16x16x32_bf16 v[14:17], v[148:151], v[208:211], v[14:17]
	v_mfma_f32_16x16x32_bf16 v[10:13], v[156:159], v[208:211], v[10:13]
	s_setprio 0
	s_setprio 1
	v_mfma_f32_16x16x32_bf16 v[54:57], v[160:163], v[176:179], v[54:57]
	v_mfma_f32_16x16x32_bf16 v[50:53], v[168:171], v[176:179], v[50:53]
	v_mfma_f32_16x16x32_bf16 v[38:41], v[160:163], v[184:187], v[38:41]
	v_mfma_f32_16x16x32_bf16 v[34:37], v[168:171], v[184:187], v[34:37]
	v_mfma_f32_16x16x32_bf16 v[22:25], v[160:163], v[196:199], v[22:25]
	v_mfma_f32_16x16x32_bf16 v[18:21], v[168:171], v[196:199], v[18:21]
	v_mfma_f32_16x16x32_bf16 v[6:9], v[160:163], v[204:207], v[6:9]
	v_mfma_f32_16x16x32_bf16 v[2:5], v[168:171], v[204:207], v[2:5]
	v_mfma_f32_16x16x32_bf16 v[54:57], v[164:167], v[180:183], v[54:57]
	v_mfma_f32_16x16x32_bf16 v[50:53], v[172:175], v[180:183], v[50:53]
	v_mfma_f32_16x16x32_bf16 v[38:41], v[164:167], v[192:195], v[38:41]
	v_mfma_f32_16x16x32_bf16 v[34:37], v[172:175], v[192:195], v[34:37]
	v_mfma_f32_16x16x32_bf16 v[22:25], v[164:167], v[200:203], v[22:25]
	v_mfma_f32_16x16x32_bf16 v[18:21], v[172:175], v[200:203], v[18:21]
	v_mfma_f32_16x16x32_bf16 v[6:9], v[164:167], v[208:211], v[6:9]
	v_mfma_f32_16x16x32_bf16 v[2:5], v[172:175], v[208:211], v[2:5]
	s_setprio 0
	s_barrier
	s_add_i32 s1, 0, 0x18000
	s_add_i32 s63, 0, 0x1c000
	v_add_u32_e32 v156, s1, v142
	v_add_u32_e32 v172, s63, v142
	ds_read_b128 v[144:147], v156
	ds_read_b128 v[148:151], v156 offset:1024
	ds_read_b128 v[152:155], v156 offset:2048
	ds_read_b128 v[156:159], v156 offset:3072
	ds_read_b128 v[160:163], v172
	ds_read_b128 v[164:167], v172 offset:1024
	ds_read_b128 v[168:171], v172 offset:2048
	ds_read_b128 v[172:175], v172 offset:3072
	s_add_u32 s48, s52, s26
	s_addc_u32 s49, s53, s27
	s_mov_b32 m0, s55
	v_lshl_add_u64 v[246:247], s[48:49], 0, v[134:135]
	ds_read_b128 v[176:179], v143 offset:32768
	ds_read_b128 v[180:183], v143 offset:33792
	ds_read_b128 v[184:187], v143 offset:34816
	ds_read_b128 v[192:195], v143 offset:35840
	ds_read_b128 v[196:199], v143 offset:36864
	ds_read_b128 v[200:203], v143 offset:37888
	ds_read_b128 v[204:207], v143 offset:38912
	ds_read_b128 v[208:211], v143 offset:39936
	global_load_lds_dwordx4 v[246:247], off
	v_lshl_add_u64 v[246:247], s[48:49], 0, v[132:133]
	s_mov_b32 m0, s56
	s_nop 0
	global_load_lds_dwordx4 v[246:247], off
	s_waitcnt vmcnt(8)
	s_waitcnt lgkmcnt(0)
	s_barrier
	s_setprio 1
	s_waitcnt lgkmcnt(0)
	v_mfma_f32_16x16x32_bf16 v[122:125], v[144:147], v[176:179], v[122:125]
	v_mfma_f32_16x16x32_bf16 v[126:129], v[152:155], v[176:179], v[126:129]
	v_mfma_f32_16x16x32_bf16 v[110:113], v[144:147], v[184:187], v[110:113]
	v_mfma_f32_16x16x32_bf16 v[106:109], v[152:155], v[184:187], v[106:109]
	v_mfma_f32_16x16x32_bf16 v[94:97], v[144:147], v[196:199], v[94:97]
	v_mfma_f32_16x16x32_bf16 v[90:93], v[152:155], v[196:199], v[90:93]
	v_mfma_f32_16x16x32_bf16 v[78:81], v[144:147], v[204:207], v[78:81]
	v_mfma_f32_16x16x32_bf16 v[74:77], v[152:155], v[204:207], v[74:77]
	v_mfma_f32_16x16x32_bf16 v[122:125], v[148:151], v[180:183], v[122:125]
	v_mfma_f32_16x16x32_bf16 v[126:129], v[156:159], v[180:183], v[126:129]
	v_mfma_f32_16x16x32_bf16 v[110:113], v[148:151], v[192:195], v[110:113]
	v_mfma_f32_16x16x32_bf16 v[106:109], v[156:159], v[192:195], v[106:109]
	v_mfma_f32_16x16x32_bf16 v[94:97], v[148:151], v[200:203], v[94:97]
	v_mfma_f32_16x16x32_bf16 v[90:93], v[156:159], v[200:203], v[90:93]
	v_mfma_f32_16x16x32_bf16 v[78:81], v[148:151], v[208:211], v[78:81]
	v_mfma_f32_16x16x32_bf16 v[74:77], v[156:159], v[208:211], v[74:77]
	s_setprio 0
	s_setprio 1
	v_mfma_f32_16x16x32_bf16 v[118:121], v[160:163], v[176:179], v[118:121]
	v_mfma_f32_16x16x32_bf16 v[114:117], v[168:171], v[176:179], v[114:117]
	v_mfma_f32_16x16x32_bf16 v[102:105], v[160:163], v[184:187], v[102:105]
	v_mfma_f32_16x16x32_bf16 v[98:101], v[168:171], v[184:187], v[98:101]
	v_mfma_f32_16x16x32_bf16 v[86:89], v[160:163], v[196:199], v[86:89]
	v_mfma_f32_16x16x32_bf16 v[82:85], v[168:171], v[196:199], v[82:85]
	v_mfma_f32_16x16x32_bf16 v[70:73], v[160:163], v[204:207], v[70:73]
	v_mfma_f32_16x16x32_bf16 v[66:69], v[168:171], v[204:207], v[66:69]
	v_mfma_f32_16x16x32_bf16 v[118:121], v[164:167], v[180:183], v[118:121]
	v_mfma_f32_16x16x32_bf16 v[114:117], v[172:175], v[180:183], v[114:117]
	v_mfma_f32_16x16x32_bf16 v[102:105], v[164:167], v[192:195], v[102:105]
	v_mfma_f32_16x16x32_bf16 v[98:101], v[172:175], v[192:195], v[98:101]
	v_mfma_f32_16x16x32_bf16 v[86:89], v[164:167], v[200:203], v[86:89]
	v_mfma_f32_16x16x32_bf16 v[82:85], v[172:175], v[200:203], v[82:85]
	v_mfma_f32_16x16x32_bf16 v[70:73], v[164:167], v[208:211], v[70:73]
	v_mfma_f32_16x16x32_bf16 v[66:69], v[172:175], v[208:211], v[66:69]
	s_setprio 0
	s_barrier
; #define PG8_STAGE(bufoff, gbase, voff) do { _Pragma("unroll") for (int _i = 0; _i < 2; ++_i) \
;         __builtin_amdgcn_global_load_lds((const unsigned*)((const char*)(gbase) + (voff)[_i]), (LAS unsigned*)(lds + (bufoff) + ldsw + _i * 8192), 16, 0, 0); } while (0)
; #define PG8_LDA(dst, b, h) do { _Pragma("unroll") for (int m = 0; m < 4; ++m) _Pragma("unroll") for (int k = 0; k < 2; ++k) dst[m][k] = *(const LAS bf16x8*)(lds + PG8_SA(b, h) + aoff + m * 2048 + k * 1024); } while (0)
; #define PG8_MMA(ai, bj, At, Bt) do { __builtin_amdgcn_s_setprio(1); _Pragma("unroll") for (int m = 0; m < 4; ++m) _Pragma("unroll") for (int n = 0; n < 2; ++n) _Pragma("unroll") for (int k = 0; k < 2; ++k) \
;         acc[ai][bj][m][n] = __builtin_amdgcn_mfma_f32_16x16x32_bf16(Bt[n][k], At[m][k], acc[ai][bj][m][n], 0, 0, 0); __builtin_amdgcn_s_setprio(0); } while (0)
; #define PG8_WAIT_V(n) asm volatile("s_waitcnt vmcnt(" #n ")" ::: "memory")
; #define PG8_WAIT_L(n) asm volatile("s_waitcnt lgkmcnt(" #n ")" ::: "memory")
; #define PG8_BAR __builtin_amdgcn_s_barrier()
; #define PG8_SCHED __builtin_amdgcn_sched_barrier(0)
; template <class Epi, class Sched>
; __device__ __forceinline__ void gemm_phase(LAS unsigned char* lds, const Gemm g, const Sched& S, const Epi& E) {
;     ...
;             PG8_LDA(At, 1, 1); PG8_STAGE(PG8_SB(1, 0), b3, voffB); PG8_STAGE(PG8_SB(1, 1), b3 + hstep, voffB); PG8_STAGE(PG8_SA(1, 0), a3, voffA);
;             PG8_WAIT_V(8); PG8_WAIT_L(0); PG8_BAR; PG8_MMA(1, 0, At, B0); PG8_MMA(1, 1, At, B1); PG8_BAR; PG8_SCHED;
;         }
	s_add_i32 s1, s1, s4
	v_lshl_add_u64 v[212:213], v[212:213], 0, s[6:7]
	s_mov_b32 m0, s1
	ds_read_b128 v[176:179], v143 offset:49152
	ds_read_b128 v[180:183], v143 offset:50176
	ds_read_b128 v[184:187], v143 offset:51200
	ds_read_b128 v[192:195], v143 offset:52224
	ds_read_b128 v[196:199], v143 offset:53248
	ds_read_b128 v[200:203], v143 offset:54272
	ds_read_b128 v[204:207], v143 offset:55296
	ds_read_b128 v[208:211], v143 offset:56320
	global_load_lds_dwordx4 v[212:213], off
	v_lshl_add_u64 v[212:213], v[214:215], 0, s[6:7]
	s_add_i32 m0, s1, 0x2000
	s_add_i32 s1, s63, s4
	global_load_lds_dwordx4 v[212:213], off
	v_lshl_add_u64 v[212:213], v[216:217], 0, s[6:7]
	s_mov_b32 m0, s1
	s_nop 0
	global_load_lds_dwordx4 v[212:213], off
	v_lshl_add_u64 v[212:213], v[238:239], 0, s[6:7]
	s_add_i32 m0, s1, 0x2000
	s_nop 0
	global_load_lds_dwordx4 v[212:213], off
	v_lshl_add_u64 v[212:213], v[240:241], 0, s[6:7]
	s_mov_b32 m0, s57
	s_nop 0
	global_load_lds_dwordx4 v[212:213], off
	v_lshl_add_u64 v[212:213], v[244:245], 0, s[6:7]
	s_mov_b32 m0, s58
	s_nop 0
	global_load_lds_dwordx4 v[212:213], off
	s_waitcnt vmcnt(8)
	s_waitcnt lgkmcnt(0)
	s_barrier
	s_setprio 1
	s_waitcnt lgkmcnt(0)
	v_mfma_f32_16x16x32_bf16 v[62:65], v[144:147], v[176:179], v[62:65]
	v_mfma_f32_16x16x32_bf16 v[58:61], v[152:155], v[176:179], v[58:61]
	v_mfma_f32_16x16x32_bf16 v[46:49], v[144:147], v[184:187], v[46:49]
	v_mfma_f32_16x16x32_bf16 v[42:45], v[152:155], v[184:187], v[42:45]
	v_mfma_f32_16x16x32_bf16 v[30:33], v[144:147], v[196:199], v[30:33]
	v_mfma_f32_16x16x32_bf16 v[26:29], v[152:155], v[196:199], v[26:29]
	v_mfma_f32_16x16x32_bf16 v[14:17], v[144:147], v[204:207], v[14:17]
	v_mfma_f32_16x16x32_bf16 v[10:13], v[152:155], v[204:207], v[10:13]
	v_mfma_f32_16x16x32_bf16 v[62:65], v[148:151], v[180:183], v[62:65]
	v_mfma_f32_16x16x32_bf16 v[58:61], v[156:159], v[180:183], v[58:61]
	v_mfma_f32_16x16x32_bf16 v[46:49], v[148:151], v[192:195], v[46:49]
	v_mfma_f32_16x16x32_bf16 v[42:45], v[156:159], v[192:195], v[42:45]
	v_mfma_f32_16x16x32_bf16 v[30:33], v[148:151], v[200:203], v[30:33]
	v_mfma_f32_16x16x32_bf16 v[26:29], v[156:159], v[200:203], v[26:29]
	v_mfma_f32_16x16x32_bf16 v[14:17], v[148:151], v[208:211], v[14:17]
	v_mfma_f32_16x16x32_bf16 v[10:13], v[156:159], v[208:211], v[10:13]
	s_setprio 0
	s_setprio 1
	v_mfma_f32_16x16x32_bf16 v[54:57], v[160:163], v[176:179], v[54:57]
	v_mfma_f32_16x16x32_bf16 v[50:53], v[168:171], v[176:179], v[50:53]
	v_mfma_f32_16x16x32_bf16 v[38:41], v[160:163], v[184:187], v[38:41]
	v_mfma_f32_16x16x32_bf16 v[34:37], v[168:171], v[184:187], v[34:37]
	v_mfma_f32_16x16x32_bf16 v[22:25], v[160:163], v[196:199], v[22:25]
	v_mfma_f32_16x16x32_bf16 v[18:21], v[168:171], v[196:199], v[18:21]
	v_mfma_f32_16x16x32_bf16 v[6:9], v[160:163], v[204:207], v[6:9]
	v_mfma_f32_16x16x32_bf16 v[2:5], v[168:171], v[204:207], v[2:5]
	v_mfma_f32_16x16x32_bf16 v[54:57], v[164:167], v[180:183], v[54:57]
	v_mfma_f32_16x16x32_bf16 v[50:53], v[172:175], v[180:183], v[50:53]
	v_mfma_f32_16x16x32_bf16 v[38:41], v[164:167], v[192:195], v[38:41]
	v_mfma_f32_16x16x32_bf16 v[34:37], v[172:175], v[192:195], v[34:37]
	v_mfma_f32_16x16x32_bf16 v[22:25], v[164:167], v[200:203], v[22:25]
	v_mfma_f32_16x16x32_bf16 v[18:21], v[172:175], v[200:203], v[18:21]
	v_mfma_f32_16x16x32_bf16 v[6:9], v[164:167], v[208:211], v[6:9]
	v_mfma_f32_16x16x32_bf16 v[2:5], v[172:175], v[208:211], v[2:5]
	s_setprio 0
	s_barrier
	s_cmp_ge_i32 s62, s59
	s_mov_b64 s[48:49], s[50:51]
	s_mov_b32 s52, s62
	s_cbranch_scc0 .LBB0_435

; __device__ __forceinline__ unsigned cvt_pk_bf16(float lo, float hi) { unsigned r; asm volatile("v_cvt_pk_bf16_f32 %0, %1, %2" : "=v"(r) : "v"(lo), "v"(hi)); return r; }
; #define PG8_OPQ(p) asm volatile("" : "+v"(p))
;     __device__ __forceinline__ void operator()(const f32x4 (&acc)[2][2][4][2], const Unit& u, int wr, int wc, int fr, int fq) const {
;         char* p = (char*)(O + (size_t)(wr * 64 + fr) * ldc + u.pn * BM + wc * 32 + 8 * fq);
;         const size_t step = (size_t)16 * ldc * 2;
; #pragma unroll
;         for (int ai = 0; ai < 2; ++ai) {
; #pragma unroll
;             for (int m = 0; m < 4; ++m) {
;                 PG8_OPQ(p);
; #pragma unroll
;                 for (int bj = 0; bj < 2; ++bj) { f32x4 v0 = acc[ai][bj][m][0], v1 = acc[ai][bj][m][1];
;                     if (ACT == 1) {
; #pragma unroll
;                         for (int j = 0; j < 4; ++j) { const float a0 = fmaxf(v0[j], 0.f), a1 = fmaxf(v1[j], 0.f); v0[j] = a0 * a0; v1[j] = a1 * a1; } }
;                     u32x4 w; w.x = cvt_pk_bf16(v0[0], v0[1]); w.y = cvt_pk_bf16(v0[2], v0[3]); w.z = cvt_pk_bf16(v1[0], v1[1]); w.w = cvt_pk_bf16(v1[2], v1[3]);
;                     *(u32x4*)(p + bj * HALF * 2) = w; }
;                 p += step;
.LBB0_438:
	v_max_f32_e32 v122, v122, v122
	s_lshr_b32 s36, s8, 2
	s_lshl_b32 s36, s36, 23
	s_and_b32 s99, s8, 3
	s_lshl_b32 s99, s99, 8
	s_add_u32 s36, s36, s99
	s_lshr_b32 s99, s98, 14
	s_add_u32 s36, s36, s99
	v_max_f32_e32 v122, 0, v122
	v_max_f32_e32 v123, v123, v123
	v_max_f32_e32 v124, v124, v124
	v_max_f32_e32 v125, v125, v125
	v_lshl_add_u64 v[144:145], s[36:37], 1, v[136:137]
	v_max_f32_e32 v126, v126, v126
	v_mul_f32_e32 v122, v122, v122
	v_max_f32_e32 v123, 0, v123
	v_max_f32_e32 v127, v127, v127
	v_max_f32_e32 v124, 0, v124
	v_max_f32_e32 v128, v128, v128
	v_max_f32_e32 v125, 0, v125
	v_max_f32_e32 v129, v129, v129
	v_max_f32_e32 v114, v114, v114
	v_max_f32_e32 v115, v115, v115
	v_max_f32_e32 v116, v116, v116
	v_max_f32_e32 v126, 0, v126
	v_max_f32_e32 v127, 0, v127
	v_mul_f32_e32 v123, v123, v123
	v_max_f32_e32 v128, 0, v128
	v_mul_f32_e32 v124, v124, v124
	v_max_f32_e32 v129, 0, v129
	v_mul_f32_e32 v125, v125, v125
	v_cvt_pk_bf16_f32 v122, v122, v123
	v_max_f32_e32 v114, 0, v114
	v_max_f32_e32 v115, 0, v115
	v_max_f32_e32 v116, 0, v116
	v_mul_f32_e32 v126, v126, v126
	v_mul_f32_e32 v127, v127, v127
	v_mul_f32_e32 v128, v128, v128
	v_mul_f32_e32 v129, v129, v129
	v_cvt_pk_bf16_f32 v123, v124, v125
	v_cvt_pk_bf16_f32 v124, v126, v127
	v_cvt_pk_bf16_f32 v125, v128, v129
	flat_store_dwordx4 v[144:145], v[122:125]
	v_max_f32_e32 v118, v118, v118
	v_max_f32_e32 v117, v117, v117
	v_mul_f32_e32 v122, v114, v114
	v_max_f32_e32 v114, v119, v119
	v_mul_f32_e32 v119, v115, v115
	v_max_f32_e32 v115, v120, v120
	v_mul_f32_e32 v120, v116, v116
	v_max_f32_e32 v116, v121, v121
	v_max_f32_e32 v114, 0, v114
	v_max_f32_e32 v115, 0, v115
	v_max_f32_e32 v116, 0, v116
	v_max_f32_e32 v118, 0, v118
	v_mul_f32_e32 v114, v114, v114
	v_mul_f32_e32 v115, v115, v115
	v_max_f32_e32 v117, 0, v117
	v_mul_f32_e32 v116, v116, v116
	v_max_f32_e32 v106, v106, v106
	v_mul_f32_e32 v118, v118, v118
	v_mul_f32_e32 v117, v117, v117
	v_cvt_pk_bf16_f32 v114, v118, v114
	v_cvt_pk_bf16_f32 v115, v115, v116
	v_cvt_pk_bf16_f32 v116, v122, v119
	v_max_f32_e32 v106, 0, v106
	v_max_f32_e32 v107, v107, v107
	v_max_f32_e32 v108, v108, v108
	v_cvt_pk_bf16_f32 v117, v120, v117
	flat_store_dwordx4 v[144:145], v[114:117] offset:256
	v_max_f32_e32 v107, 0, v107
	v_max_f32_e32 v108, 0, v108
	v_mul_f32_e32 v116, v106, v106
	v_max_f32_e32 v106, v111, v111
	v_max_f32_e32 v110, v110, v110
	v_max_f32_e32 v106, 0, v106
	v_mul_f32_e32 v111, v107, v107
	v_max_f32_e32 v107, v112, v112
	v_mul_f32_e32 v112, v108, v108
	v_max_f32_e32 v108, v113, v113
	v_max_f32_e32 v109, v109, v109
	v_lshl_add_u64 v[114:115], v[144:145], 0, s[16:17]
	v_max_f32_e32 v110, 0, v110
	v_mul_f32_e32 v106, v106, v106
	v_max_f32_e32 v107, 0, v107
	v_max_f32_e32 v108, 0, v108
	v_max_f32_e32 v109, 0, v109
	v_max_f32_e32 v98, v98, v98
	v_max_f32_e32 v99, v99, v99
	v_max_f32_e32 v100, v100, v100
	v_mul_f32_e32 v110, v110, v110
	v_mul_f32_e32 v107, v107, v107
	v_mul_f32_e32 v108, v108, v108
	v_mul_f32_e32 v109, v109, v109
	v_cvt_pk_bf16_f32 v106, v110, v106
	v_max_f32_e32 v98, 0, v98
	v_max_f32_e32 v99, 0, v99
	v_max_f32_e32 v100, 0, v100
	v_cvt_pk_bf16_f32 v107, v107, v108
	v_cvt_pk_bf16_f32 v108, v116, v111
	v_cvt_pk_bf16_f32 v109, v112, v109
	flat_store_dwordx4 v[114:115], v[106:109]
	v_max_f32_e32 v102, v102, v102
	v_max_f32_e32 v101, v101, v101
	v_mul_f32_e32 v106, v98, v98
	v_max_f32_e32 v98, v103, v103
	v_mul_f32_e32 v103, v99, v99
	v_max_f32_e32 v99, v104, v104
	v_mul_f32_e32 v104, v100, v100
	v_max_f32_e32 v100, v105, v105
	v_max_f32_e32 v98, 0, v98
	v_max_f32_e32 v99, 0, v99
	v_max_f32_e32 v100, 0, v100
	v_max_f32_e32 v102, 0, v102
	v_mul_f32_e32 v98, v98, v98
	v_mul_f32_e32 v99, v99, v99
	v_max_f32_e32 v101, 0, v101
	v_mul_f32_e32 v100, v100, v100
	v_max_f32_e32 v90, v90, v90
	v_mul_f32_e32 v102, v102, v102
	v_mul_f32_e32 v101, v101, v101
	v_cvt_pk_bf16_f32 v98, v102, v98
	v_cvt_pk_bf16_f32 v99, v99, v100
	v_cvt_pk_bf16_f32 v100, v106, v103
	v_max_f32_e32 v90, 0, v90
	v_max_f32_e32 v91, v91, v91
	v_max_f32_e32 v92, v92, v92
	v_cvt_pk_bf16_f32 v101, v104, v101
	flat_store_dwordx4 v[114:115], v[98:101] offset:256
	v_max_f32_e32 v91, 0, v91
	v_max_f32_e32 v92, 0, v92
	v_mul_f32_e32 v100, v90, v90
	v_max_f32_e32 v90, v95, v95
	v_max_f32_e32 v94, v94, v94
	v_max_f32_e32 v90, 0, v90
	v_mul_f32_e32 v95, v91, v91
	v_max_f32_e32 v91, v96, v96
	v_mul_f32_e32 v96, v92, v92
	v_max_f32_e32 v92, v97, v97
	v_max_f32_e32 v93, v93, v93
	v_lshl_add_u64 v[98:99], v[114:115], 0, s[16:17]
	v_max_f32_e32 v94, 0, v94
	v_mul_f32_e32 v90, v90, v90
	v_max_f32_e32 v91, 0, v91
	v_max_f32_e32 v92, 0, v92
	v_max_f32_e32 v93, 0, v93
	v_max_f32_e32 v82, v82, v82
	v_max_f32_e32 v83, v83, v83
	v_max_f32_e32 v84, v84, v84
	v_mul_f32_e32 v94, v94, v94
	v_mul_f32_e32 v91, v91, v91
	v_mul_f32_e32 v92, v92, v92
	v_mul_f32_e32 v93, v93, v93
	v_cvt_pk_bf16_f32 v90, v94, v90
	v_max_f32_e32 v82, 0, v82
	v_max_f32_e32 v83, 0, v83
	v_max_f32_e32 v84, 0, v84
	v_cvt_pk_bf16_f32 v91, v91, v92
	v_cvt_pk_bf16_f32 v92, v100, v95
	v_cvt_pk_bf16_f32 v93, v96, v93
	flat_store_dwordx4 v[98:99], v[90:93]
	v_max_f32_e32 v86, v86, v86
	v_max_f32_e32 v85, v85, v85
	v_mul_f32_e32 v90, v82, v82
	v_max_f32_e32 v82, v87, v87
	v_mul_f32_e32 v87, v83, v83
	v_max_f32_e32 v83, v88, v88
	v_mul_f32_e32 v88, v84, v84
	v_max_f32_e32 v84, v89, v89
	v_max_f32_e32 v82, 0, v82
	v_max_f32_e32 v83, 0, v83
	v_max_f32_e32 v84, 0, v84
	v_max_f32_e32 v86, 0, v86
	v_mul_f32_e32 v82, v82, v82
	v_mul_f32_e32 v83, v83, v83
	v_max_f32_e32 v85, 0, v85
	v_mul_f32_e32 v84, v84, v84
	v_max_f32_e32 v74, v74, v74
	v_mul_f32_e32 v86, v86, v86
	v_mul_f32_e32 v85, v85, v85
	v_cvt_pk_bf16_f32 v82, v86, v82
; __device__ __forceinline__ unsigned cvt_pk_bf16(float lo, float hi) { unsigned r; asm volatile("v_cvt_pk_bf16_f32 %0, %1, %2" : "=v"(r) : "v"(lo), "v"(hi)); return r; }
; #define PG8_OPQ(p) asm volatile("" : "+v"(p))
;     __device__ __forceinline__ void operator()(const f32x4 (&acc)[2][2][4][2], const Unit& u, int wr, int wc, int fr, int fq) const {
;     ...
;         for (int ai = 0; ai < 2; ++ai) {
; #pragma unroll
;             for (int m = 0; m < 4; ++m) {
;                 PG8_OPQ(p);
; #pragma unroll
;                 for (int bj = 0; bj < 2; ++bj) { f32x4 v0 = acc[ai][bj][m][0], v1 = acc[ai][bj][m][1];
;                     if (ACT == 1) {
; #pragma unroll
;                         for (int j = 0; j < 4; ++j) { const float a0 = fmaxf(v0[j], 0.f), a1 = fmaxf(v1[j], 0.f); v0[j] = a0 * a0; v1[j] = a1 * a1; } }
;                     u32x4 w; w.x = cvt_pk_bf16(v0[0], v0[1]); w.y = cvt_pk_bf16(v0[2], v0[3]); w.z = cvt_pk_bf16(v1[0], v1[1]); w.w = cvt_pk_bf16(v1[2], v1[3]);
;                     *(u32x4*)(p + bj * HALF * 2) = w; }
;                 p += step;
	v_cvt_pk_bf16_f32 v83, v83, v84
	v_cvt_pk_bf16_f32 v84, v90, v87
	v_max_f32_e32 v74, 0, v74
	v_max_f32_e32 v75, v75, v75
	v_max_f32_e32 v76, v76, v76
	v_cvt_pk_bf16_f32 v85, v88, v85
	flat_store_dwordx4 v[98:99], v[82:85] offset:256
	v_max_f32_e32 v75, 0, v75
	v_max_f32_e32 v76, 0, v76
	v_mul_f32_e32 v84, v74, v74
	v_max_f32_e32 v74, v79, v79
	v_max_f32_e32 v78, v78, v78
	v_max_f32_e32 v74, 0, v74
	v_mul_f32_e32 v79, v75, v75
	v_max_f32_e32 v75, v80, v80
	v_mul_f32_e32 v80, v76, v76
	v_max_f32_e32 v76, v81, v81
	v_max_f32_e32 v77, v77, v77
	v_lshl_add_u64 v[82:83], v[98:99], 0, s[16:17]
	v_max_f32_e32 v78, 0, v78
	v_mul_f32_e32 v74, v74, v74
	v_max_f32_e32 v75, 0, v75
	v_max_f32_e32 v76, 0, v76
	v_max_f32_e32 v77, 0, v77
	v_max_f32_e32 v66, v66, v66
	v_max_f32_e32 v67, v67, v67
	v_max_f32_e32 v68, v68, v68
	v_mul_f32_e32 v78, v78, v78
	v_mul_f32_e32 v75, v75, v75
	v_mul_f32_e32 v76, v76, v76
	v_mul_f32_e32 v77, v77, v77
	v_cvt_pk_bf16_f32 v74, v78, v74
	v_max_f32_e32 v66, 0, v66
	v_max_f32_e32 v67, 0, v67
	v_max_f32_e32 v68, 0, v68
	v_cvt_pk_bf16_f32 v75, v75, v76
	v_cvt_pk_bf16_f32 v76, v84, v79
	v_cvt_pk_bf16_f32 v77, v80, v77
	flat_store_dwordx4 v[82:83], v[74:77]
	v_max_f32_e32 v70, v70, v70
	v_max_f32_e32 v69, v69, v69
	v_mul_f32_e32 v74, v66, v66
	v_max_f32_e32 v66, v71, v71
	v_mul_f32_e32 v71, v67, v67
	v_max_f32_e32 v67, v72, v72
	v_mul_f32_e32 v72, v68, v68
	v_max_f32_e32 v68, v73, v73
	v_max_f32_e32 v66, 0, v66
	v_max_f32_e32 v67, 0, v67
	v_max_f32_e32 v68, 0, v68
	v_max_f32_e32 v70, 0, v70
	v_mul_f32_e32 v66, v66, v66
	v_mul_f32_e32 v67, v67, v67
	v_max_f32_e32 v69, 0, v69
	v_mul_f32_e32 v68, v68, v68
	v_max_f32_e32 v58, v58, v58
	v_mul_f32_e32 v70, v70, v70
	v_mul_f32_e32 v69, v69, v69
	v_cvt_pk_bf16_f32 v66, v70, v66
	v_cvt_pk_bf16_f32 v67, v67, v68
	v_cvt_pk_bf16_f32 v68, v74, v71
	v_max_f32_e32 v58, 0, v58
	v_max_f32_e32 v59, v59, v59
	v_max_f32_e32 v60, v60, v60
	v_cvt_pk_bf16_f32 v69, v72, v69
	flat_store_dwordx4 v[82:83], v[66:69] offset:256
	v_max_f32_e32 v59, 0, v59
	v_max_f32_e32 v60, 0, v60
	v_mul_f32_e32 v68, v58, v58
	v_max_f32_e32 v58, v63, v63
	s_mov_b64 s[48:49], 0xa0000
	v_max_f32_e32 v62, v62, v62
	v_max_f32_e32 v58, 0, v58
	v_mul_f32_e32 v63, v59, v59
	v_max_f32_e32 v59, v64, v64
	v_mul_f32_e32 v64, v60, v60
	v_max_f32_e32 v60, v65, v65
	v_max_f32_e32 v61, v61, v61
	v_lshl_add_u64 v[66:67], v[82:83], 0, s[48:49]
	v_max_f32_e32 v62, 0, v62
	v_mul_f32_e32 v58, v58, v58
	v_max_f32_e32 v59, 0, v59
	v_max_f32_e32 v60, 0, v60
	v_max_f32_e32 v61, 0, v61
	v_max_f32_e32 v50, v50, v50
	v_max_f32_e32 v51, v51, v51
	v_max_f32_e32 v52, v52, v52
	v_mul_f32_e32 v62, v62, v62
	v_mul_f32_e32 v59, v59, v59
	v_mul_f32_e32 v60, v60, v60
	v_mul_f32_e32 v61, v61, v61
	v_cvt_pk_bf16_f32 v58, v62, v58
	v_max_f32_e32 v50, 0, v50
	v_max_f32_e32 v51, 0, v51
	v_max_f32_e32 v52, 0, v52
	v_cvt_pk_bf16_f32 v59, v59, v60
	v_cvt_pk_bf16_f32 v60, v68, v63
	v_cvt_pk_bf16_f32 v61, v64, v61
	flat_store_dwordx4 v[66:67], v[58:61]
	v_max_f32_e32 v54, v54, v54
	v_max_f32_e32 v53, v53, v53
	v_mul_f32_e32 v58, v50, v50
	v_max_f32_e32 v50, v55, v55
	v_mul_f32_e32 v55, v51, v51
	v_max_f32_e32 v51, v56, v56
	v_mul_f32_e32 v56, v52, v52
	v_max_f32_e32 v52, v57, v57
	v_max_f32_e32 v50, 0, v50
	v_max_f32_e32 v51, 0, v51
	v_max_f32_e32 v52, 0, v52
	v_max_f32_e32 v54, 0, v54
	v_mul_f32_e32 v50, v50, v50
	v_mul_f32_e32 v51, v51, v51
	v_max_f32_e32 v53, 0, v53
	v_mul_f32_e32 v52, v52, v52
	v_max_f32_e32 v42, v42, v42
	v_mul_f32_e32 v54, v54, v54
	v_mul_f32_e32 v53, v53, v53
	v_cvt_pk_bf16_f32 v50, v54, v50
	v_cvt_pk_bf16_f32 v51, v51, v52
	v_cvt_pk_bf16_f32 v52, v58, v55
	v_max_f32_e32 v42, 0, v42
	v_max_f32_e32 v43, v43, v43
	v_max_f32_e32 v44, v44, v44
	v_cvt_pk_bf16_f32 v53, v56, v53
	flat_store_dwordx4 v[66:67], v[50:53] offset:256
	v_max_f32_e32 v43, 0, v43
	v_max_f32_e32 v44, 0, v44
	v_mul_f32_e32 v52, v42, v42
	v_max_f32_e32 v42, v47, v47
	v_max_f32_e32 v46, v46, v46
	v_max_f32_e32 v42, 0, v42
	v_mul_f32_e32 v47, v43, v43
	v_max_f32_e32 v43, v48, v48
	v_mul_f32_e32 v48, v44, v44
	v_max_f32_e32 v44, v49, v49
	v_max_f32_e32 v45, v45, v45
	v_lshl_add_u64 v[50:51], v[66:67], 0, s[16:17]
	v_max_f32_e32 v46, 0, v46
	v_mul_f32_e32 v42, v42, v42
	v_max_f32_e32 v43, 0, v43
	v_max_f32_e32 v44, 0, v44
	v_max_f32_e32 v45, 0, v45
	v_max_f32_e32 v34, v34, v34
	v_max_f32_e32 v35, v35, v35
	v_max_f32_e32 v36, v36, v36
	v_mul_f32_e32 v46, v46, v46
	v_mul_f32_e32 v43, v43, v43
	v_mul_f32_e32 v44, v44, v44
	v_mul_f32_e32 v45, v45, v45
	v_cvt_pk_bf16_f32 v42, v46, v42
	v_max_f32_e32 v34, 0, v34
	v_max_f32_e32 v35, 0, v35
	v_max_f32_e32 v36, 0, v36
	v_cvt_pk_bf16_f32 v43, v43, v44
	v_cvt_pk_bf16_f32 v44, v52, v47
	v_cvt_pk_bf16_f32 v45, v48, v45
	flat_store_dwordx4 v[50:51], v[42:45]
	v_max_f32_e32 v38, v38, v38
	v_max_f32_e32 v37, v37, v37
	v_mul_f32_e32 v42, v34, v34
	v_max_f32_e32 v34, v39, v39
	v_mul_f32_e32 v39, v35, v35
; __device__ __forceinline__ unsigned cvt_pk_bf16(float lo, float hi) { unsigned r; asm volatile("v_cvt_pk_bf16_f32 %0, %1, %2" : "=v"(r) : "v"(lo), "v"(hi)); return r; }
; #define PG8_OPQ(p) asm volatile("" : "+v"(p))
; __device__ __forceinline__ void block_fence() { __builtin_amdgcn_fence(__ATOMIC_RELEASE, "workgroup"); __syncthreads(); __builtin_amdgcn_fence(__ATOMIC_ACQUIRE, "workgroup"); }
; #define PHASE_PTRS() CArgs* ka = kargs(); unsigned char* ws = ka->ws; unsigned char* PB = ws + WS_PANEL + (size_t)panel * PANEL_BYTES; \
;         bf16_t* HBp = (bf16_t*)(ws + WS_HB) + (size_t)panel * 256 * DM; float* Hp = ka->out + (size_t)panel * 256 * DM; (void)PB; (void)HBp; (void)Hp
;     __device__ __forceinline__ void operator()(const f32x4 (&acc)[2][2][4][2], const Unit& u, int wr, int wc, int fr, int fq) const {
;     ...
;         for (int ai = 0; ai < 2; ++ai) {
; #pragma unroll
;             for (int m = 0; m < 4; ++m) {
;                 PG8_OPQ(p);
; #pragma unroll
;                 for (int bj = 0; bj < 2; ++bj) { f32x4 v0 = acc[ai][bj][m][0], v1 = acc[ai][bj][m][1];
;                     if (ACT == 1) {
; #pragma unroll
;                         for (int j = 0; j < 4; ++j) { const float a0 = fmaxf(v0[j], 0.f), a1 = fmaxf(v1[j], 0.f); v0[j] = a0 * a0; v1[j] = a1 * a1; } }
;                     u32x4 w; w.x = cvt_pk_bf16(v0[0], v0[1]); w.y = cvt_pk_bf16(v0[2], v0[3]); w.z = cvt_pk_bf16(v1[0], v1[1]); w.w = cvt_pk_bf16(v1[2], v1[3]);
;                     *(u32x4*)(p + bj * HALF * 2) = w; }
;                 p += step;
;             }
;             p += 4 * step;
; __global__ void __launch_bounds__(512, 2) fwd_megakernel(Args a) {
;     ...
;         block_fence();
;         {
;             PHASE_PTRS();
;             pg8::Gemm g{(const bf16_t*)(PB + P_HID), (const bf16_t*)(ws + WS_W2) + (size_t)l * DM * DFF, DFF}; pg8::PanelOrder S{DM / 256};
	v_max_f32_e32 v35, v40, v40
	v_mul_f32_e32 v40, v36, v36
	v_max_f32_e32 v36, v41, v41
	v_max_f32_e32 v34, 0, v34
	v_max_f32_e32 v35, 0, v35
	v_max_f32_e32 v36, 0, v36
	v_max_f32_e32 v38, 0, v38
	v_mul_f32_e32 v34, v34, v34
	v_mul_f32_e32 v35, v35, v35
	v_max_f32_e32 v37, 0, v37
	v_mul_f32_e32 v36, v36, v36
	v_max_f32_e32 v26, v26, v26
	v_mul_f32_e32 v38, v38, v38
	v_mul_f32_e32 v37, v37, v37
	v_cvt_pk_bf16_f32 v34, v38, v34
	v_cvt_pk_bf16_f32 v35, v35, v36
	v_cvt_pk_bf16_f32 v36, v42, v39
	v_max_f32_e32 v26, 0, v26
	v_max_f32_e32 v27, v27, v27
	v_max_f32_e32 v28, v28, v28
	v_cvt_pk_bf16_f32 v37, v40, v37
	flat_store_dwordx4 v[50:51], v[34:37] offset:256
	v_max_f32_e32 v27, 0, v27
	v_max_f32_e32 v28, 0, v28
	v_mul_f32_e32 v36, v26, v26
	v_max_f32_e32 v26, v31, v31
	v_max_f32_e32 v30, v30, v30
	v_max_f32_e32 v26, 0, v26
	v_mul_f32_e32 v31, v27, v27
	v_max_f32_e32 v27, v32, v32
	v_mul_f32_e32 v32, v28, v28
	v_max_f32_e32 v28, v33, v33
	v_max_f32_e32 v29, v29, v29
	v_lshl_add_u64 v[34:35], v[50:51], 0, s[16:17]
	v_max_f32_e32 v30, 0, v30
	v_mul_f32_e32 v26, v26, v26
	v_max_f32_e32 v27, 0, v27
	v_max_f32_e32 v28, 0, v28
	v_max_f32_e32 v29, 0, v29
	v_max_f32_e32 v18, v18, v18
	v_max_f32_e32 v19, v19, v19
	v_max_f32_e32 v20, v20, v20
	v_mul_f32_e32 v30, v30, v30
	v_mul_f32_e32 v27, v27, v27
	v_mul_f32_e32 v28, v28, v28
	v_mul_f32_e32 v29, v29, v29
	v_cvt_pk_bf16_f32 v26, v30, v26
	v_max_f32_e32 v18, 0, v18
	v_max_f32_e32 v19, 0, v19
	v_max_f32_e32 v20, 0, v20
	v_cvt_pk_bf16_f32 v27, v27, v28
	v_cvt_pk_bf16_f32 v28, v36, v31
	v_cvt_pk_bf16_f32 v29, v32, v29
	flat_store_dwordx4 v[34:35], v[26:29]
	v_max_f32_e32 v22, v22, v22
	v_max_f32_e32 v21, v21, v21
	v_mul_f32_e32 v26, v18, v18
	v_max_f32_e32 v18, v23, v23
	v_mul_f32_e32 v23, v19, v19
	v_max_f32_e32 v19, v24, v24
	v_mul_f32_e32 v24, v20, v20
	v_max_f32_e32 v20, v25, v25
	v_max_f32_e32 v18, 0, v18
	v_max_f32_e32 v19, 0, v19
	v_max_f32_e32 v20, 0, v20
	v_max_f32_e32 v22, 0, v22
	v_mul_f32_e32 v18, v18, v18
	v_mul_f32_e32 v19, v19, v19
	v_max_f32_e32 v21, 0, v21
	v_mul_f32_e32 v20, v20, v20
	v_max_f32_e32 v10, v10, v10
	v_mul_f32_e32 v22, v22, v22
	v_mul_f32_e32 v21, v21, v21
	v_cvt_pk_bf16_f32 v18, v22, v18
	v_cvt_pk_bf16_f32 v19, v19, v20
	v_cvt_pk_bf16_f32 v20, v26, v23
	v_max_f32_e32 v10, 0, v10
	v_max_f32_e32 v11, v11, v11
	v_max_f32_e32 v12, v12, v12
	v_cvt_pk_bf16_f32 v21, v24, v21
	flat_store_dwordx4 v[34:35], v[18:21] offset:256
	v_max_f32_e32 v11, 0, v11
	v_max_f32_e32 v12, 0, v12
	v_mul_f32_e32 v20, v10, v10
	v_max_f32_e32 v10, v15, v15
	v_max_f32_e32 v14, v14, v14
	v_max_f32_e32 v10, 0, v10
	v_mul_f32_e32 v15, v11, v11
	v_max_f32_e32 v11, v16, v16
	v_mul_f32_e32 v16, v12, v12
	v_max_f32_e32 v12, v17, v17
	v_max_f32_e32 v13, v13, v13
	v_lshl_add_u64 v[18:19], v[34:35], 0, s[16:17]
	v_max_f32_e32 v14, 0, v14
	v_mul_f32_e32 v10, v10, v10
	v_max_f32_e32 v11, 0, v11
	v_max_f32_e32 v12, 0, v12
	v_max_f32_e32 v13, 0, v13
	v_max_f32_e32 v2, v2, v2
	v_max_f32_e32 v3, v3, v3
	v_max_f32_e32 v4, v4, v4
	v_mul_f32_e32 v14, v14, v14
	v_mul_f32_e32 v11, v11, v11
	v_mul_f32_e32 v12, v12, v12
	v_mul_f32_e32 v13, v13, v13
	v_cvt_pk_bf16_f32 v10, v14, v10
	v_max_f32_e32 v2, 0, v2
	v_max_f32_e32 v3, 0, v3
	v_max_f32_e32 v4, 0, v4
	v_cvt_pk_bf16_f32 v11, v11, v12
	v_cvt_pk_bf16_f32 v12, v20, v15
	v_cvt_pk_bf16_f32 v13, v16, v13
	flat_store_dwordx4 v[18:19], v[10:13]
	v_max_f32_e32 v5, v5, v5
	v_max_f32_e32 v6, v6, v6
	v_mul_f32_e32 v10, v2, v2
	v_max_f32_e32 v2, v7, v7
	v_mul_f32_e32 v7, v3, v3
	v_max_f32_e32 v3, v8, v8
	v_mul_f32_e32 v8, v4, v4
	v_max_f32_e32 v4, v9, v9
	v_max_f32_e32 v2, 0, v2
	v_max_f32_e32 v3, 0, v3
	v_max_f32_e32 v4, 0, v4
	v_max_f32_e32 v5, 0, v5
	v_max_f32_e32 v6, 0, v6
	v_mul_f32_e32 v2, v2, v2
	v_mul_f32_e32 v3, v3, v3
	v_mul_f32_e32 v4, v4, v4
	v_mul_f32_e32 v5, v5, v5
	s_cmp_eq_u32 s8, 15
	s_mov_b64 s[8:9], -1
	v_mul_f32_e32 v6, v6, v6
	v_cvt_pk_bf16_f32 v2, v6, v2
	v_cvt_pk_bf16_f32 v3, v3, v4
	v_cvt_pk_bf16_f32 v4, v10, v7
	v_cvt_pk_bf16_f32 v5, v8, v5
	flat_store_dwordx4 v[18:19], v[2:5] offset:256
	s_cbranch_scc1 .LBB0_430
	s_andn2_b64 vcc, exec, s[38:39]
	s_cbranch_vccnz .LBB0_429
	s_barrier
	s_branch .LBB0_429
.LBB0_441:
	v_readlane_b32 s2, v249, 0
	v_readlane_b32 s3, v249, 1
	v_mov_b32_e32 v15, v189
	s_waitcnt vmcnt(0)
	s_barrier
	s_waitcnt vmcnt(0) lgkmcnt(0)
	s_barrier
	v_readfirstlane_b32 s98, v189
	s_nop 3
	s_cmp_ge_u32 s98, 64
	s_cbranch_scc1 .Lgrp_bar1_done
	s_lshr_b32 s98, s88, 21
	s_and_b32 s99, s98, 7
	s_lshr_b32 s98, s98, 5
	s_lshl_b32 s98, s98, 3
	s_or_b32 s98, s98, s99
	s_lshl_b32 s98, s98, 5
	v_readlane_b32 s99, v248, 36
	s_nop 3
	s_lshl_b32 s99, s99, 4
	s_add_u32 s98, s98, s99
	s_add_u32 s98, s98, 14340
	v_mov_b32_e32 v2, s98
	v_mov_b32_e32 v3, 1
	s_mov_b64 s[100:101], exec
	s_mov_b64 exec, 1
	buffer_wbl2 sc1
	s_waitcnt vmcnt(0)
	global_atomic_add v2, v3, s[80:81]
	s_mov_b32 s99, 0

; __device__ __forceinline__ void block_fence() { __builtin_amdgcn_fence(__ATOMIC_RELEASE, "workgroup"); __syncthreads(); __builtin_amdgcn_fence(__ATOMIC_ACQUIRE, "workgroup"); }
; __global__ void __launch_bounds__(512, 2) fwd_megakernel(Args a) {
;     ...
;         block_fence();
.LBB0_456:
	v_readlane_b32 s2, v249, 0
	v_readlane_b32 s3, v249, 1
	s_waitcnt vmcnt(0)
	s_barrier
	s_waitcnt lgkmcnt(0)
	s_barrier
	v_readfirstlane_b32 s98, v189
	s_nop 3
	s_cmp_ge_u32 s98, 64
	s_cbranch_scc1 .Lgrp_bar2_done
	s_lshr_b32 s98, s88, 21
	s_and_b32 s99, s98, 7
	s_lshr_b32 s98, s98, 5
	s_lshl_b32 s98, s98, 3
	s_or_b32 s98, s98, s99
	s_lshl_b32 s98, s98, 5
	v_readlane_b32 s99, v248, 36
	s_nop 3
	s_lshl_b32 s99, s99, 4
	s_add_u32 s98, s98, s99
	s_add_u32 s98, s98, 14344
	v_mov_b32_e32 v2, s98
	v_mov_b32_e32 v3, 1
	s_mov_b64 s[100:101], exec
	s_mov_b64 exec, 1
	buffer_wbl2 sc1
	s_waitcnt vmcnt(0)
	global_atomic_add v2, v3, s[80:81]
	s_mov_b32 s99, 0
